# adds: pmat Q/K loads pipelined 8-deep + 4-deep K-fragment LDS prefetch; loop-invariant norm gains hoisted out of norm2/final/mla-rowpass row loops (removes store->load->wait serialization)
# speedup vs baseline: 1.0075x; 1.0041x over previous
; #define GAS __attribute__((address_space(1)))
; __device__ __forceinline__ float bf_lo(unsigned w) { return __uint_as_float(w << 16); }
; __device__ __forceinline__ float bf_hi(unsigned w) { return __uint_as_float(w & 0xffff0000u); }
; __device__ __forceinline__ unsigned char* arg_ws(const Frame& F) { return (unsigned char*)arg_in(F, AW_WS / 2); }
; __device__ __forceinline__ void mla_rowpass_phase(const Frame& F, int j, const bf16_t* CQKV, bf16_t* CN, bf16_t* KR, int rows, int grow0) {
;     const float* gq = arg_in(F, 13) + (size_t)j * 512; const float* gkv = arg_in(F, 16) + (size_t)j * 512; unsigned char* ws = arg_ws(F);
;     const float* cosM = (const float*)(ws + TAB_COSM); const float* sinM = (const float*)(ws + TAB_SINM);
;     for (int r = F.gw; r < rows; r += F.NGW) {
;         const bf16_t* src = CQKV + (size_t)r * MA_N;
;         const u32x4 wq = *(const GAS u32x4*)(src + F.lane * 8), wk = *(const GAS u32x4*)(src + 512 + F.lane * 8);
;         float q[8], k[8]; float sq = 0.f, sk = 0.f;
; #pragma unroll
;         for (int e = 0; e < 4; ++e) { q[2 * e] = bf_lo(wq[e]); q[2 * e + 1] = bf_hi(wq[e]); k[2 * e] = bf_lo(wk[e]); k[2 * e + 1] = bf_hi(wk[e]);
;             sq += q[2 * e] * q[2 * e] + q[2 * e + 1] * q[2 * e + 1]; sk += k[2 * e] * k[2 * e] + k[2 * e + 1] * k[2 * e + 1]; }
;         const float rq = 1.0f / sqrtf(wave_sum(sq) * (1.f / 512.f) + NORM_EPS), rk = 1.0f / sqrtf(wave_sum(sk) * (1.f / 512.f) + NORM_EPS);
;         const f32x4 gq0 = *((const GAS f32x4*)gq + 2 * F.lane), gq1 = *((const GAS f32x4*)gq + 2 * F.lane + 1), gk0 = *((const GAS f32x4*)gkv + 2 * F.lane), gk1 = *((const GAS f32x4*)gkv + 2 * F.lane + 1);
.LBB0_351:
	v_readlane_b32 s0, v254, 3
	s_cmp_ge_i32 s10, s0
	v_readlane_b32 s1, v254, 4
	s_cselect_b64 s[22:23], -1, 0
	s_and_b64 s[0:1], s[22:23], s[28:29]
	s_andn2_b64 vcc, exec, s[0:1]
	s_cbranch_vccnz .LBB0_361
	s_mov_b32 s0, -1
	v_readlane_b32 s1, v254, 2
	v_mbcnt_lo_u32_b32 v0, s0, 0
	v_mbcnt_hi_u32_b32 v0, s0, v0
	v_readlane_b32 s0, v254, 5
	v_mov_b32_e32 v1, v193
	s_add_i32 s10, 0, 0x23b00
	v_add_u32_e32 v0, s0, v0
	s_lshl_b32 s1, s1, 3
	v_add_u32_e32 v2, 0, v1
	v_add_u32_e32 v3, 0x23ba8, v2
	ds_read_b32 v4, v3
	v_readfirstlane_b32 s0, v0
	s_ashr_i32 s0, s0, 6
	s_add_i32 s28, s1, s0
	v_add_u32_e32 v1, s10, v1
	s_waitcnt lgkmcnt(0)
	v_readfirstlane_b32 s0, v4
	v_add_u32_e32 v4, 0x23bac, v2
	ds_read_b32 v5, v4
	s_cmp_gt_i32 s28, 0x105ff
	s_waitcnt lgkmcnt(0)
	v_readfirstlane_b32 s1, v5
	v_add_u32_e32 v5, 0x23ba0, v2
	ds_read_b32 v6, v5
	v_add_u32_e32 v2, 0x23ba4, v2
	s_waitcnt lgkmcnt(0)
	v_readfirstlane_b32 s10, v6
	ds_read_b32 v6, v2
	ds_read_b32 v5, v5
	ds_read_b32 v2, v2
	s_waitcnt lgkmcnt(0)
	v_readfirstlane_b32 s11, v6
	s_waitcnt lgkmcnt(1)
	v_readfirstlane_b32 s12, v5
	s_waitcnt lgkmcnt(0)
	v_readfirstlane_b32 s13, v2
	ds_read_b32 v2, v1 offset:104
	s_waitcnt lgkmcnt(0)
	v_readfirstlane_b32 s18, v2
	ds_read_b32 v2, v1 offset:108
	s_waitcnt lgkmcnt(0)
	v_readfirstlane_b32 s29, v2
	ds_read_b32 v2, v1 offset:128
	ds_read_b32 v1, v1 offset:132
	s_waitcnt lgkmcnt(0)
	v_readfirstlane_b32 s38, v2
	s_waitcnt lgkmcnt(0)
	v_readfirstlane_b32 s39, v1
	ds_read_b32 v1, v3
	s_waitcnt lgkmcnt(0)
	v_readfirstlane_b32 s36, v1
	ds_read_b32 v1, v4
	s_waitcnt lgkmcnt(0)
	v_readfirstlane_b32 s37, v1
	s_cbranch_scc1 .LBB0_361
	s_add_u32 s30, s36, 0x904000
	s_addc_u32 s31, s37, 0
	s_add_u32 s36, s36, 0xa04800
	v_readlane_b32 s40, v255, 37
	s_addc_u32 s37, s37, 0
	s_lshl_b32 s40, s40, 10
	s_and_b32 s40, s40, 0x800
	s_add_u32 s38, s38, s40
	s_addc_u32 s39, s39, 0
	v_and_b32_e32 v16, 63, v0
	v_readlane_b32 s41, v255, 38
	s_add_u32 s40, s18, s40
	s_addc_u32 s41, s29, 0
	v_lshlrev_b32_e32 v192, 5, v16
	s_ashr_i32 s29, s28, 31
	v_lshl_add_u64 v[20:21], s[38:39], 0, v[192:193]
	s_lshl_b64 s[38:39], s[28:29], 7
	s_add_u32 s12, s12, s38
	v_lshl_add_u64 v[18:19], s[40:41], 0, v[192:193]
	v_lshlrev_b32_e32 v192, 2, v16
	s_addc_u32 s13, s13, s39
	v_lshl_add_u64 v[0:1], s[12:13], 0, v[192:193]
	s_mov_b64 s[12:13], 0x10600000
	v_lshl_add_u64 v[22:23], v[0:1], 0, s[12:13]
	s_lshl_b64 s[12:13], s[28:29], 11
	s_add_u32 s38, s0, s12
	s_addc_u32 s39, s1, s13
	s_mul_i32 s1, s28, 0xa00
	s_mul_hi_i32 s0, s28, 0xa00
	s_add_u32 s1, s10, s1
	s_addc_u32 s0, s11, s0
	s_add_u32 s40, s1, 0x10f00800
	v_cmp_gt_u32_e64 s[34:35], 32, v16
	v_lshlrev_b32_e32 v24, 4, v16
	v_mov_b32_e32 v25, v193
	s_addc_u32 s41, s0, 0
	s_mov_b32 s12, 0xf800000
	global_load_dwordx4 v[64:67], v[18:19], off offset:16
	global_load_dwordx4 v[68:71], v[18:19], off
	global_load_dwordx4 v[72:75], v[20:21], off offset:16
	global_load_dwordx4 v[76:79], v[20:21], off
	s_branch .LBB0_356

; #define GAS __attribute__((address_space(1)))
; __device__ __forceinline__ unsigned cvt_pk_bf16(float lo, float hi) { unsigned r; asm volatile("v_cvt_pk_bf16_f32 %0, %1, %2" : "=v"(r) : "v"(lo), "v"(hi)); return r; }
; __device__ __forceinline__ float bf_lo(unsigned w) { return __uint_as_float(w << 16); }
; __device__ __forceinline__ float bf_hi(unsigned w) { return __uint_as_float(w & 0xffff0000u); }
; __device__ __forceinline__ void mla_rowpass_phase(const Frame& F, int j, const bf16_t* CQKV, bf16_t* CN, bf16_t* KR, int rows, int grow0) {
;     ...
;     for (int r = F.gw; r < rows; r += F.NGW) {
;         const bf16_t* src = CQKV + (size_t)r * MA_N;
;         const u32x4 wq = *(const GAS u32x4*)(src + F.lane * 8), wk = *(const GAS u32x4*)(src + 512 + F.lane * 8);
;         float q[8], k[8]; float sq = 0.f, sk = 0.f;
; #pragma unroll
;         for (int e = 0; e < 4; ++e) { q[2 * e] = bf_lo(wq[e]); q[2 * e + 1] = bf_hi(wq[e]); k[2 * e] = bf_lo(wk[e]); k[2 * e + 1] = bf_hi(wk[e]);
;             sq += q[2 * e] * q[2 * e] + q[2 * e + 1] * q[2 * e + 1]; sk += k[2 * e] * k[2 * e] + k[2 * e + 1] * k[2 * e + 1]; }
;         const float rq = 1.0f / sqrtf(wave_sum(sq) * (1.f / 512.f) + NORM_EPS), rk = 1.0f / sqrtf(wave_sum(sk) * (1.f / 512.f) + NORM_EPS);
;         const f32x4 gq0 = *((const GAS f32x4*)gq + 2 * F.lane), gq1 = *((const GAS f32x4*)gq + 2 * F.lane + 1), gk0 = *((const GAS f32x4*)gkv + 2 * F.lane), gk1 = *((const GAS f32x4*)gkv + 2 * F.lane + 1);
;         u32x4 oq, ok;
;         oq.x = cvt_pk_bf16(q[0] * rq * gq0[0], q[1] * rq * gq0[1]); oq.y = cvt_pk_bf16(q[2] * rq * gq0[2], q[3] * rq * gq0[3]); oq.z = cvt_pk_bf16(q[4] * rq * gq1[0], q[5] * rq * gq1[1]); oq.w = cvt_pk_bf16(q[6] * rq * gq1[2], q[7] * rq * gq1[3]);
;         ok.x = cvt_pk_bf16(k[0] * rk * gk0[0], k[1] * rk * gk0[1]); ok.y = cvt_pk_bf16(k[2] * rk * gk0[2], k[3] * rk * gk0[3]); ok.z = cvt_pk_bf16(k[4] * rk * gk1[0], k[5] * rk * gk1[1]); ok.w = cvt_pk_bf16(k[6] * rk * gk1[2], k[7] * rk * gk1[3]);
;         *(GAS u32x4*)(CN + (size_t)r * 1024 + F.lane * 8) = oq; *(GAS u32x4*)(CN + (size_t)r * 1024 + 512 + F.lane * 8) = ok;
;         if (F.lane < 32) {
;             const unsigned w = *(const GAS unsigned*)(src + 1024 + 2 * F.lane); int t = row_tpos(grow0 + r); t = t < 0 ? 0 : t;
.LBB0_356:
	v_lshl_add_u64 v[4:5], s[40:41], 0, v[24:25]
	global_load_dwordx4 v[0:3], v[4:5], off offset:-2048
	s_nop 0
	global_load_dwordx4 v[4:7], v[4:5], off offset:-1024
	s_waitcnt vmcnt(0)
	v_lshlrev_b32_e32 v32, 16, v0
	v_lshlrev_b32_e32 v36, 16, v1
	v_and_b32_e32 v31, 0xffff0000, v0
	v_mul_f32_e32 v0, v32, v32
	v_and_b32_e32 v35, 0xffff0000, v1
	v_mul_f32_e32 v1, v36, v36
	v_lshlrev_b32_e32 v39, 16, v2
	v_lshlrev_b32_e32 v26, 16, v4
	v_fmac_f32_e32 v0, v31, v31
	v_lshlrev_b32_e32 v28, 16, v5
	v_fmac_f32_e32 v1, v35, v35
	v_and_b32_e32 v38, 0xffff0000, v2
	v_mul_f32_e32 v2, v39, v39
	v_and_b32_e32 v17, 0xffff0000, v4
	v_mul_f32_e32 v4, v26, v26
	v_and_b32_e32 v27, 0xffff0000, v5
	v_add_f32_e32 v0, v0, v1
	v_mul_f32_e32 v1, v28, v28
	v_lshlrev_b32_e32 v30, 16, v6
	v_fmac_f32_e32 v2, v38, v38
	v_fmac_f32_e32 v4, v17, v17
	v_fmac_f32_e32 v1, v27, v27
	v_and_b32_e32 v29, 0xffff0000, v6
	v_add_f32_e32 v0, v2, v0
	v_mul_f32_e32 v2, v30, v30
	v_add_f32_e32 v1, v4, v1
	v_fmac_f32_e32 v2, v29, v29
	v_lshlrev_b32_e32 v40, 16, v3
	v_add_f32_e32 v1, v2, v1
	v_and_b32_e32 v37, 0xffff0000, v3
	v_mul_f32_e32 v2, v40, v40
	v_lshlrev_b32_e32 v34, 16, v7
	v_fmac_f32_e32 v2, v37, v37
	v_and_b32_e32 v33, 0xffff0000, v7
	v_add_f32_e32 v0, v2, v0
	v_mul_f32_e32 v2, v34, v34
	v_fmac_f32_e32 v2, v33, v33
	v_add_f32_e32 v1, v2, v1
	ds_swizzle_b32 v2, v0 offset:swizzle(SWAP,1)
	s_waitcnt lgkmcnt(0)
	v_add_f32_e32 v0, v0, v2
	ds_swizzle_b32 v2, v0 offset:swizzle(SWAP,2)
	s_waitcnt lgkmcnt(0)
	v_add_f32_e32 v0, v0, v2
	ds_swizzle_b32 v2, v0 offset:swizzle(SWAP,4)
	s_waitcnt lgkmcnt(0)
	v_add_f32_e32 v0, v0, v2
	ds_swizzle_b32 v2, v0 offset:swizzle(SWAP,8)
	s_waitcnt lgkmcnt(0)
	v_add_f32_e32 v0, v0, v2
	ds_swizzle_b32 v2, v0 offset:swizzle(SWAP,16)
	s_waitcnt lgkmcnt(0)
	v_add_f32_e32 v0, v0, v2
	v_mov_b32_e32 v2, v0
	s_nop 1
	v_permlane32_swap_b32_e32 v0, v2
	v_add_f32_e32 v0, v0, v2
	v_fmamk_f32 v0, v0, 0x3b000000, v250
	v_cmp_gt_f32_e32 vcc, s12, v0
	v_mul_f32_e32 v2, 0x4f800000, v0
	s_nop 0
	v_cndmask_b32_e32 v0, v0, v2, vcc
	v_sqrt_f32_e32 v2, v0
	s_nop 0
	v_add_u32_e32 v3, -1, v2
	v_fma_f32 v4, -v3, v2, v0
	v_cmp_ge_f32_e64 s[0:1], 0, v4
	v_add_u32_e32 v4, 1, v2
	s_nop 0
	v_cndmask_b32_e64 v3, v2, v3, s[0:1]
	v_fma_f32 v2, -v4, v2, v0
	v_cmp_lt_f32_e64 s[0:1], 0, v2
	s_nop 1
	v_cndmask_b32_e64 v2, v3, v4, s[0:1]
	v_mul_f32_e32 v3, 0x37800000, v2
	v_cndmask_b32_e32 v2, v2, v3, vcc
	v_cmp_class_f32_e32 vcc, v0, v251
	s_nop 1
	v_cndmask_b32_e32 v0, v2, v0, vcc
	v_div_scale_f32 v2, s[0:1], v0, v0, 1.0
	v_rcp_f32_e32 v3, v2
	s_nop 0
	v_fma_f32 v4, -v2, v3, 1.0
	v_fmac_f32_e32 v3, v4, v3
	v_div_scale_f32 v4, vcc, 1.0, v0, 1.0
	v_mul_f32_e32 v5, v4, v3
	v_fma_f32 v6, -v2, v5, v4
	v_fmac_f32_e32 v5, v6, v3
	v_fma_f32 v2, -v2, v5, v4
	v_div_fmas_f32 v2, v2, v3, v5
	v_div_fixup_f32 v41, v2, v0, 1.0
	ds_swizzle_b32 v0, v1 offset:swizzle(SWAP,1)
	v_mul_f32_e32 v32, v41, v32
	v_mul_f32_e32 v31, v41, v31
	s_waitcnt lgkmcnt(0)
	v_add_f32_e32 v0, v1, v0
	ds_swizzle_b32 v1, v0 offset:swizzle(SWAP,2)
	s_waitcnt lgkmcnt(0)
	v_add_f32_e32 v0, v0, v1
	ds_swizzle_b32 v1, v0 offset:swizzle(SWAP,4)
	s_waitcnt lgkmcnt(0)
	v_add_f32_e32 v0, v0, v1
	ds_swizzle_b32 v1, v0 offset:swizzle(SWAP,8)
	s_waitcnt lgkmcnt(0)
	v_add_f32_e32 v0, v0, v1
	ds_swizzle_b32 v1, v0 offset:swizzle(SWAP,16)
	s_waitcnt lgkmcnt(0)
	v_add_f32_e32 v0, v0, v1
	v_mov_b32_e32 v1, v0
	s_nop 1
	v_permlane32_swap_b32_e32 v0, v1
	v_add_f32_e32 v0, v0, v1
	v_fmamk_f32 v0, v0, 0x3b000000, v250
	v_cmp_gt_f32_e32 vcc, s12, v0
	v_mul_f32_e32 v1, 0x4f800000, v0
	s_nop 0
	v_cndmask_b32_e32 v0, v0, v1, vcc
	v_sqrt_f32_e32 v1, v0
	s_nop 0
	v_add_u32_e32 v2, -1, v1
	v_fma_f32 v3, -v2, v1, v0
	v_cmp_ge_f32_e64 s[0:1], 0, v3
	v_add_u32_e32 v3, 1, v1
	s_nop 0
	v_cndmask_b32_e64 v2, v1, v2, s[0:1]
	v_fma_f32 v1, -v3, v1, v0
	v_cmp_lt_f32_e64 s[0:1], 0, v1
	s_nop 1
	v_cndmask_b32_e64 v1, v2, v3, s[0:1]
	v_mul_f32_e32 v2, 0x37800000, v1
	v_cndmask_b32_e32 v1, v1, v2, vcc
	v_cmp_class_f32_e32 vcc, v0, v251
	s_nop 1
	v_cndmask_b32_e32 v0, v1, v0, vcc
	v_div_scale_f32 v1, s[0:1], v0, v0, 1.0
	v_rcp_f32_e32 v2, v1
	s_nop 0
	v_fma_f32 v3, -v1, v2, 1.0
	v_fmac_f32_e32 v2, v3, v2
	v_div_scale_f32 v3, vcc, 1.0, v0, 1.0
	v_mul_f32_e32 v4, v3, v2
	v_fma_f32 v5, -v1, v4, v3
	v_fmac_f32_e32 v4, v5, v2
	v_fma_f32 v1, -v1, v4, v3
	v_div_fmas_f32 v1, v1, v2, v4
	v_div_fixup_f32 v42, v1, v0, 1.0
	v_mul_f32_e32 v12, v32, v68
	v_mul_f32_e32 v13, v31, v69
	v_cvt_pk_bf16_f32 v12, v12, v13
	v_mul_f32_e32 v13, v41, v36
	v_mul_f32_e32 v13, v13, v70
	v_mul_f32_e32 v14, v41, v35
	v_mul_f32_e32 v14, v14, v71
	v_cvt_pk_bf16_f32 v13, v13, v14
	v_mul_f32_e32 v14, v41, v39
	v_mul_f32_e32 v8, v14, v64
	v_mul_f32_e32 v14, v41, v38
	v_mul_f32_e32 v9, v14, v65
	v_cvt_pk_bf16_f32 v14, v8, v9
	v_mul_f32_e32 v8, v41, v40
	v_mul_f32_e32 v8, v8, v66
	v_mul_f32_e32 v9, v41, v37
	v_mul_f32_e32 v9, v9, v67
	v_cvt_pk_bf16_f32 v15, v8, v9
	v_mul_f32_e32 v8, v42, v26
	v_mul_f32_e32 v4, v76, v8
	v_mul_f32_e32 v8, v42, v17
	v_mul_f32_e32 v5, v77, v8
	v_cvt_pk_bf16_f32 v4, v4, v5
	v_mul_f32_e32 v5, v42, v28
	v_mul_f32_e32 v5, v78, v5
	v_mul_f32_e32 v6, v42, v27
	v_mul_f32_e32 v6, v79, v6
	v_cvt_pk_bf16_f32 v5, v5, v6
	v_mul_f32_e32 v6, v42, v30
	v_mul_f32_e32 v0, v72, v6
	v_mul_f32_e32 v6, v42, v29
	v_mul_f32_e32 v1, v73, v6
	v_cvt_pk_bf16_f32 v6, v0, v1
	v_mul_f32_e32 v0, v42, v34
	v_mul_f32_e32 v1, v42, v33
	v_mul_f32_e32 v0, v74, v0
	v_mul_f32_e32 v1, v75, v1
	v_cvt_pk_bf16_f32 v7, v0, v1
	v_lshl_add_u64 v[0:1], s[38:39], 0, v[24:25]
	v_add_co_u32_e32 v0, vcc, 0x11300000, v0
	s_nop 1
	v_addc_co_u32_e32 v1, vcc, 0, v1, vcc
	global_store_dwordx4 v[0:1], v[12:15], off
	global_store_dwordx4 v[0:1], v[4:7], off offset:1024
	s_and_saveexec_b64 s[0:1], s[34:35]
	s_cbranch_execz .LBB0_355
	v_lshl_add_u64 v[0:1], s[40:41], 0, v[192:193]
	global_load_dword v0, v[0:1], off
	s_cmp_gt_i32 s28, 0x81ff
	s_mov_b64 s[42:43], -1
	s_cbranch_scc0 .LBB0_359
	s_add_i32 s10, s28, 0x7e00
	s_and_b32 s11, s10, 0xffff
	s_mul_i32 s11, s11, 0xf83f
	s_lshr_b32 s11, s11, 28
	s_mulk_i32 s11, 0x1080
	s_sub_i32 s10, s10, s11
	s_and_b32 s10, s10, 0xffff
	s_mov_b64 s[42:43], 0

; #define GAS __attribute__((address_space(1)))
; #define LAS __attribute__((address_space(3)))
; __device__ __forceinline__ unsigned cvt_pk_bf16(float lo, float hi) { unsigned r; asm volatile("v_cvt_pk_bf16_f32 %0, %1, %2" : "=v"(r) : "v"(lo), "v"(hi)); return r; }
; __device__ __forceinline__ unsigned argw(const Frame& F, int w) { return ((const volatile LAS unsigned*)(F.lds + ARGS_OFF + F.zero))[w]; }
; __device__ __forceinline__ void pmat_phase(const Frame& F, const bf16_t* Q, const bf16_t* K, bf16_t* PB, int half) {
;     ...
;     for (int u = F.vcu; u < nunits; u += F.G) {
;         const int head = u & 7, sc = u >> 3;
;         const float lgf = __uint_as_float(__builtin_amdgcn_readfirstlane(argw(F, AW_LG2 + head))), lgb = __uint_as_float(__builtin_amdgcn_readfirstlane(argw(F, AW_LG2 + 8 + head)));
;         const size_t u0 = (size_t)sc * 128 * 2048 + head * 256; const unsigned lq = (unsigned)(srow * 2048 + scc * 8);
; #pragma unroll
;         for (int ii = 0; ii < 8; ++ii) { const u32x4 qv = *(const GAS u32x4*)(Q + u0 + (size_t)ii * 16 * 2048 + lq), kv = *(const GAS u32x4*)(K + u0 + (size_t)ii * 16 * 2048 + lq);
;             *(LAS u32x4*)(lg + (srow + 16 * ii) * PS + scc * 16) = qv; *(LAS u32x4*)(lg + 128 * PS + (srow + 16 * ii) * PS + scc * 16) = kv; }
;         __syncthreads();
;         bf16x8 Qf[8];
; #pragma unroll
;         for (int ks = 0; ks < 8; ++ks) Qf[ks] = *(const LAS bf16x8*)(bQown + 64 * ks);
;         bf16_t* pout = PB + (size_t)u * 16384; const unsigned lpo = (unsigned)((16 * wv + l15) * 128 + 4 * quad); const int i_abs = 16 * wv + l15;
; #pragma unroll
;         for (int jt = 0; jt < 8; ++jt) { f32x4 st = {0.f, 0.f, 0.f, 0.f};
; #pragma unroll
;             for (int ks = 0; ks < 8; ++ks) { const bf16x8 Kf = *(const LAS bf16x8*)(bK + 16 * jt * PS + 64 * ks); st = __builtin_amdgcn_mfma_f32_16x16x32_bf16(Kf, Qf[ks], st, 0, 0, 0); }
; #pragma unroll
;             for (int r = 0; r < 4; ++r) { const int jj = 16 * jt + 4 * quad + r;
;                 st[r] *= __builtin_amdgcn_exp2f(jj <= i_abs ? lgf * (float)(-jj - 1) : lgb * (float)(jj - 128)); }
;             *(GAS u32x2*)(pout + 16 * jt + lpo) = (u32x2){cvt_pk_bf16(st[0], st[1]), cvt_pk_bf16(st[2], st[3])}; }
.LBB0_915:
	s_and_b32 s13, s22, 7
	v_lshl_add_u32 v0, s13, 2, v103
	s_ashr_i32 vcc_lo, s22, 3
	ds_read_b32 v1, v0 offset:824
	ds_read_b32 v0, v0 offset:856
	s_ashr_i32 vcc_hi, vcc_lo, 31
	s_lshl_b64 vcc, vcc, 19
	s_lshl_b32 s13, s13, 9
	s_or_b32 vcc_lo, vcc_lo, s13
	v_lshl_add_u64 v[8:9], v[32:33], 0, vcc
	s_waitcnt lgkmcnt(1)
	v_readfirstlane_b32 s23, v1
	s_waitcnt lgkmcnt(0)
	v_readfirstlane_b32 s12, v0
	v_lshl_add_u64 v[10:11], v[34:35], 0, vcc
	global_load_dwordx4 v[0:3], v[8:9], off
	global_load_dwordx4 v[4:7], v[10:11], off
	v_mul_f32_e32 v107, s23, v39
	s_add_i32 s22, s22, s16
	s_cmp_lt_i32 s22, s18
	v_add_co_u32_e32 v108, vcc, s15, v8
	s_nop 1
	v_addc_co_u32_e32 v109, vcc, 0, v9, vcc
	global_load_dwordx4 v[12:15], v[108:109], off
	v_add_co_u32_e32 v110, vcc, s15, v10
	s_nop 1
	v_addc_co_u32_e32 v111, vcc, 0, v11, vcc
	global_load_dwordx4 v[16:19], v[110:111], off
	v_add_co_u32_e32 v108, vcc, s33, v8
	s_nop 1
	v_addc_co_u32_e32 v109, vcc, 0, v9, vcc
	global_load_dwordx4 v[20:23], v[108:109], off
	v_add_co_u32_e32 v110, vcc, s33, v10
	s_nop 1
	v_addc_co_u32_e32 v111, vcc, 0, v11, vcc
	global_load_dwordx4 v[24:27], v[110:111], off
	v_add_co_u32_e32 v108, vcc, s3, v8
	s_nop 1
	v_addc_co_u32_e32 v109, vcc, 0, v9, vcc
	global_load_dwordx4 v[28:31], v[108:109], off
	v_add_co_u32_e32 v110, vcc, s3, v10
	s_nop 1
	v_addc_co_u32_e32 v111, vcc, 0, v11, vcc
	global_load_dwordx4 v[112:115], v[110:111], off
	s_waitcnt vmcnt(7)
	ds_write_b128 v104, v[0:3]
	v_add_co_u32_e32 v108, vcc, s96, v8
	s_nop 1
	v_addc_co_u32_e32 v109, vcc, 0, v9, vcc
	global_load_dwordx4 v[0:3], v[108:109], off
	s_waitcnt vmcnt(7)
	ds_write_b128 v105, v[4:7]
	v_add_co_u32_e32 v110, vcc, s96, v10
	s_nop 1
	v_addc_co_u32_e32 v111, vcc, 0, v11, vcc
	global_load_dwordx4 v[4:7], v[110:111], off
	s_waitcnt vmcnt(7)
	ds_write_b128 v104, v[12:15] offset:8448
	v_add_co_u32_e32 v108, vcc, s10, v8
	s_nop 1
	v_addc_co_u32_e32 v109, vcc, 0, v9, vcc
	global_load_dwordx4 v[12:15], v[108:109], off
	s_waitcnt vmcnt(7)
	ds_write_b128 v105, v[16:19] offset:8448
	v_add_co_u32_e32 v110, vcc, s10, v10
	s_nop 1
	v_addc_co_u32_e32 v111, vcc, 0, v11, vcc
	global_load_dwordx4 v[16:19], v[110:111], off
	s_waitcnt vmcnt(7)
	ds_write_b128 v104, v[20:23] offset:16896
	v_add_co_u32_e32 v108, vcc, s28, v8
	s_nop 1
	v_addc_co_u32_e32 v109, vcc, 0, v9, vcc
	global_load_dwordx4 v[20:23], v[108:109], off
	s_waitcnt vmcnt(7)
	ds_write_b128 v105, v[24:27] offset:16896
	v_add_co_u32_e32 v110, vcc, s28, v10
	s_nop 1
	v_addc_co_u32_e32 v111, vcc, 0, v11, vcc
	global_load_dwordx4 v[24:27], v[110:111], off
	s_waitcnt vmcnt(7)
	ds_write_b128 v104, v[28:31] offset:25344
	v_add_co_u32_e32 v108, vcc, s29, v8
	s_nop 1
	v_addc_co_u32_e32 v109, vcc, 0, v9, vcc
	global_load_dwordx4 v[28:31], v[108:109], off
	s_waitcnt vmcnt(7)
	ds_write_b128 v105, v[112:115] offset:25344
	v_add_co_u32_e32 v110, vcc, s29, v10
	s_nop 1
	v_addc_co_u32_e32 v111, vcc, 0, v11, vcc
	global_load_dwordx4 v[112:115], v[110:111], off
	s_waitcnt vmcnt(7)
	ds_write_b128 v104, v[0:3] offset:33792
	s_waitcnt vmcnt(6)
	ds_write_b128 v105, v[4:7] offset:33792
	s_waitcnt vmcnt(5)
	ds_write_b128 v104, v[12:15] offset:42240
	s_waitcnt vmcnt(4)
	ds_write_b128 v105, v[16:19] offset:42240
	s_waitcnt vmcnt(3)
	ds_write_b128 v104, v[20:23] offset:50688
	s_waitcnt vmcnt(2)
	ds_write_b128 v105, v[24:27] offset:50688
	s_waitcnt vmcnt(1)
	ds_write_b128 v104, v[28:31] offset:59136
	s_waitcnt vmcnt(0)
	ds_write_b128 v105, v[112:115] offset:59136
	s_waitcnt lgkmcnt(0)
	s_barrier
	ds_read_b128 v[28:31], v106
	ds_read_b128 v[24:27], v106 offset:64
	ds_read_b128 v[20:23], v106 offset:128
	ds_read_b128 v[16:19], v106 offset:192
	ds_read_b128 v[12:15], v106 offset:256
	ds_read_b128 v[8:11], v106 offset:320
	ds_read_b128 v[4:7], v106 offset:384
	ds_read_b128 v[0:3], v106 offset:448
	ds_read_b128 v[108:111], v38
	ds_read_b128 v[112:115], v38 offset:64
	ds_read_b128 v[116:119], v38 offset:128
	ds_read_b128 v[120:123], v38 offset:192
	ds_read_b128 v[124:127], v38 offset:256
	s_waitcnt lgkmcnt(4)
	v_mfma_f32_16x16x32_bf16 v[108:111], v[108:111], v[28:31], 0
	s_waitcnt lgkmcnt(3)
	v_mfma_f32_16x16x32_bf16 v[108:111], v[112:115], v[24:27], v[108:111]
	ds_read_b128 v[112:115], v38 offset:320
	s_waitcnt lgkmcnt(3)
	v_mfma_f32_16x16x32_bf16 v[108:111], v[116:119], v[20:23], v[108:111]
	ds_read_b128 v[116:119], v38 offset:384
	s_waitcnt lgkmcnt(3)
	v_mfma_f32_16x16x32_bf16 v[108:111], v[120:123], v[16:19], v[108:111]
	ds_read_b128 v[120:123], v38 offset:448
	s_waitcnt lgkmcnt(3)
	v_mfma_f32_16x16x32_bf16 v[108:111], v[124:127], v[12:15], v[108:111]
	s_waitcnt lgkmcnt(2)
	v_mfma_f32_16x16x32_bf16 v[108:111], v[112:115], v[8:11], v[108:111]
	s_waitcnt lgkmcnt(1)
	v_mfma_f32_16x16x32_bf16 v[108:111], v[116:119], v[4:7], v[108:111]
	s_waitcnt lgkmcnt(0)
	v_mfma_f32_16x16x32_bf16 v[108:111], v[120:123], v[0:3], v[108:111]
	v_mul_f32_e32 v112, s12, v40
	v_cndmask_b32_e64 v107, v107, v112, s[0:1]
	v_exp_f32_e32 v107, v107
	v_mul_f32_e32 v112, s12, v41
	s_nop 3
	v_mul_f32_e32 v107, v107, v108
	v_mul_f32_e32 v108, s23, v42
	v_cndmask_b32_e64 v108, v112, v108, s[34:35]
	v_exp_f32_e32 v108, v108
	v_mul_f32_e32 v112, s12, v44
	v_mul_f32_e32 v108, v108, v109
	v_mul_f32_e32 v109, s23, v43
	v_cndmask_b32_e64 v109, v109, v112, s[36:37]
	v_exp_f32_e32 v109, v109
	v_mul_f32_e32 v112, s12, v46
	v_cvt_pk_bf16_f32 v108, v107, v108
	v_mul_f32_e32 v107, s23, v47
	v_mul_f32_e32 v109, v109, v110
	v_mul_f32_e32 v110, s23, v45
	v_cndmask_b32_e64 v110, v110, v112, s[38:39]
	v_exp_f32_e32 v110, v110
	s_nop 0
	v_mul_f32_e32 v110, v110, v111
	v_cvt_pk_bf16_f32 v109, v109, v110
	global_store_dwordx2 v[36:37], v[108:109], off
	ds_read_b128 v[108:111], v38 offset:8448
	ds_read_b128 v[112:115], v38 offset:8512
	ds_read_b128 v[116:119], v38 offset:8576
	ds_read_b128 v[120:123], v38 offset:8640
	ds_read_b128 v[124:127], v38 offset:8704
	s_waitcnt lgkmcnt(4)
; #define GAS __attribute__((address_space(1)))
; #define LAS __attribute__((address_space(3)))
; __device__ __forceinline__ unsigned cvt_pk_bf16(float lo, float hi) { unsigned r; asm volatile("v_cvt_pk_bf16_f32 %0, %1, %2" : "=v"(r) : "v"(lo), "v"(hi)); return r; }
; __device__ __forceinline__ void pmat_phase(const Frame& F, const bf16_t* Q, const bf16_t* K, bf16_t* PB, int half) {
;     ...
;         for (int jt = 0; jt < 8; ++jt) { f32x4 st = {0.f, 0.f, 0.f, 0.f};
; #pragma unroll
;             for (int ks = 0; ks < 8; ++ks) { const bf16x8 Kf = *(const LAS bf16x8*)(bK + 16 * jt * PS + 64 * ks); st = __builtin_amdgcn_mfma_f32_16x16x32_bf16(Kf, Qf[ks], st, 0, 0, 0); }
; #pragma unroll
;             for (int r = 0; r < 4; ++r) { const int jj = 16 * jt + 4 * quad + r;
;                 st[r] *= __builtin_amdgcn_exp2f(jj <= i_abs ? lgf * (float)(-jj - 1) : lgb * (float)(jj - 128)); }
;             *(GAS u32x2*)(pout + 16 * jt + lpo) = (u32x2){cvt_pk_bf16(st[0], st[1]), cvt_pk_bf16(st[2], st[3])}; }
	v_mfma_f32_16x16x32_bf16 v[108:111], v[108:111], v[28:31], 0
	s_waitcnt lgkmcnt(3)
	v_mfma_f32_16x16x32_bf16 v[108:111], v[112:115], v[24:27], v[108:111]
	ds_read_b128 v[112:115], v38 offset:8768
	s_waitcnt lgkmcnt(3)
	v_mfma_f32_16x16x32_bf16 v[108:111], v[116:119], v[20:23], v[108:111]
	ds_read_b128 v[116:119], v38 offset:8832
	s_waitcnt lgkmcnt(3)
	v_mfma_f32_16x16x32_bf16 v[108:111], v[120:123], v[16:19], v[108:111]
	ds_read_b128 v[120:123], v38 offset:8896
	s_waitcnt lgkmcnt(3)
	v_mfma_f32_16x16x32_bf16 v[108:111], v[124:127], v[12:15], v[108:111]
	s_waitcnt lgkmcnt(2)
	v_mfma_f32_16x16x32_bf16 v[108:111], v[112:115], v[8:11], v[108:111]
	s_waitcnt lgkmcnt(1)
	v_mfma_f32_16x16x32_bf16 v[108:111], v[116:119], v[4:7], v[108:111]
	s_waitcnt lgkmcnt(0)
	v_mfma_f32_16x16x32_bf16 v[108:111], v[120:123], v[0:3], v[108:111]
	v_mul_f32_e32 v112, s12, v48
	v_cndmask_b32_e64 v107, v107, v112, s[40:41]
	v_exp_f32_e32 v107, v107
	v_mul_f32_e32 v112, s12, v50
	s_nop 3
	v_mul_f32_e32 v107, v107, v108
	v_mul_f32_e32 v108, s23, v49
	v_cndmask_b32_e64 v108, v108, v112, s[42:43]
	v_exp_f32_e32 v108, v108
	v_mul_f32_e32 v112, s12, v52
	v_mul_f32_e32 v108, v108, v109
	v_mul_f32_e32 v109, s23, v51
	v_cndmask_b32_e64 v109, v109, v112, s[44:45]
	v_exp_f32_e32 v109, v109
	v_mul_f32_e32 v112, s12, v54
	v_cvt_pk_bf16_f32 v108, v107, v108
	v_mul_f32_e32 v107, s23, v55
	v_mul_f32_e32 v109, v109, v110
	v_mul_f32_e32 v110, s23, v53
	v_cndmask_b32_e64 v110, v110, v112, s[46:47]
	v_exp_f32_e32 v110, v110
	s_nop 0
	v_mul_f32_e32 v110, v110, v111
	v_cvt_pk_bf16_f32 v109, v109, v110
	global_store_dwordx2 v[36:37], v[108:109], off offset:32
	ds_read_b128 v[108:111], v38 offset:16896
	ds_read_b128 v[112:115], v38 offset:16960
	ds_read_b128 v[116:119], v38 offset:17024
	ds_read_b128 v[120:123], v38 offset:17088
	ds_read_b128 v[124:127], v38 offset:17152
	s_waitcnt lgkmcnt(4)
	v_mfma_f32_16x16x32_bf16 v[108:111], v[108:111], v[28:31], 0
	s_waitcnt lgkmcnt(3)
	v_mfma_f32_16x16x32_bf16 v[108:111], v[112:115], v[24:27], v[108:111]
	ds_read_b128 v[112:115], v38 offset:17216
	s_waitcnt lgkmcnt(3)
	v_mfma_f32_16x16x32_bf16 v[108:111], v[116:119], v[20:23], v[108:111]
	ds_read_b128 v[116:119], v38 offset:17280
	s_waitcnt lgkmcnt(3)
	v_mfma_f32_16x16x32_bf16 v[108:111], v[120:123], v[16:19], v[108:111]
	ds_read_b128 v[120:123], v38 offset:17344
	s_waitcnt lgkmcnt(3)
	v_mfma_f32_16x16x32_bf16 v[108:111], v[124:127], v[12:15], v[108:111]
	s_waitcnt lgkmcnt(2)
	v_mfma_f32_16x16x32_bf16 v[108:111], v[112:115], v[8:11], v[108:111]
	s_waitcnt lgkmcnt(1)
	v_mfma_f32_16x16x32_bf16 v[108:111], v[116:119], v[4:7], v[108:111]
	s_waitcnt lgkmcnt(0)
	v_mfma_f32_16x16x32_bf16 v[108:111], v[120:123], v[0:3], v[108:111]
	v_mul_f32_e32 v112, s12, v56
	v_cndmask_b32_e64 v107, v107, v112, s[48:49]
	v_exp_f32_e32 v107, v107
	v_mul_f32_e32 v112, s12, v58
	s_nop 3
	v_mul_f32_e32 v107, v107, v108
	v_mul_f32_e32 v108, s23, v57
	v_cndmask_b32_e64 v108, v108, v112, s[50:51]
	v_exp_f32_e32 v108, v108
	v_mul_f32_e32 v112, s12, v60
	v_mul_f32_e32 v108, v108, v109
	v_mul_f32_e32 v109, s23, v59
	v_cndmask_b32_e64 v109, v109, v112, s[52:53]
	v_exp_f32_e32 v109, v109
	v_mul_f32_e32 v112, s12, v62
	v_cvt_pk_bf16_f32 v108, v107, v108
	v_mul_f32_e32 v107, s23, v63
	v_mul_f32_e32 v109, v109, v110
	v_mul_f32_e32 v110, s23, v61
	v_cndmask_b32_e64 v110, v110, v112, s[54:55]
	v_exp_f32_e32 v110, v110
	s_nop 0
	v_mul_f32_e32 v110, v110, v111
	v_cvt_pk_bf16_f32 v109, v109, v110
	global_store_dwordx2 v[36:37], v[108:109], off offset:64
	ds_read_b128 v[108:111], v38 offset:25344
	ds_read_b128 v[112:115], v38 offset:25408
	ds_read_b128 v[116:119], v38 offset:25472
	ds_read_b128 v[120:123], v38 offset:25536
	ds_read_b128 v[124:127], v38 offset:25600
	s_waitcnt lgkmcnt(4)
	v_mfma_f32_16x16x32_bf16 v[108:111], v[108:111], v[28:31], 0
	s_waitcnt lgkmcnt(3)
	v_mfma_f32_16x16x32_bf16 v[108:111], v[112:115], v[24:27], v[108:111]
	ds_read_b128 v[112:115], v38 offset:25664
	s_waitcnt lgkmcnt(3)
	v_mfma_f32_16x16x32_bf16 v[108:111], v[116:119], v[20:23], v[108:111]
	ds_read_b128 v[116:119], v38 offset:25728
	s_waitcnt lgkmcnt(3)
	v_mfma_f32_16x16x32_bf16 v[108:111], v[120:123], v[16:19], v[108:111]
	ds_read_b128 v[120:123], v38 offset:25792
	s_waitcnt lgkmcnt(3)
	v_mfma_f32_16x16x32_bf16 v[108:111], v[124:127], v[12:15], v[108:111]
	s_waitcnt lgkmcnt(2)
	v_mfma_f32_16x16x32_bf16 v[108:111], v[112:115], v[8:11], v[108:111]
	s_waitcnt lgkmcnt(1)
	v_mfma_f32_16x16x32_bf16 v[108:111], v[116:119], v[4:7], v[108:111]
	s_waitcnt lgkmcnt(0)
	v_mfma_f32_16x16x32_bf16 v[108:111], v[120:123], v[0:3], v[108:111]
	v_mul_f32_e32 v112, s12, v64
	v_cndmask_b32_e64 v107, v107, v112, s[56:57]
	v_exp_f32_e32 v107, v107
	v_mul_f32_e32 v112, s12, v66
	s_nop 3
	v_mul_f32_e32 v107, v107, v108
	v_mul_f32_e32 v108, s23, v65
	v_cndmask_b32_e64 v108, v108, v112, s[58:59]
	v_exp_f32_e32 v108, v108
	v_mul_f32_e32 v112, s12, v68
	v_mul_f32_e32 v108, v108, v109
	v_mul_f32_e32 v109, s23, v67
	v_cndmask_b32_e64 v109, v109, v112, s[60:61]
	v_exp_f32_e32 v109, v109
	v_mul_f32_e32 v112, s12, v70
	v_cvt_pk_bf16_f32 v108, v107, v108
	v_mul_f32_e32 v107, s23, v71
	v_mul_f32_e32 v109, v109, v110
	v_mul_f32_e32 v110, s23, v69
	v_cndmask_b32_e64 v110, v110, v112, s[62:63]
	v_exp_f32_e32 v110, v110
	s_nop 0
	v_mul_f32_e32 v110, v110, v111
	v_cvt_pk_bf16_f32 v109, v109, v110
	global_store_dwordx2 v[36:37], v[108:109], off offset:96
	ds_read_b128 v[108:111], v38 offset:33792
	ds_read_b128 v[112:115], v38 offset:33856
	ds_read_b128 v[116:119], v38 offset:33920
	ds_read_b128 v[120:123], v38 offset:33984
	ds_read_b128 v[124:127], v38 offset:34048
	s_waitcnt lgkmcnt(4)
; #define GAS __attribute__((address_space(1)))
; #define LAS __attribute__((address_space(3)))
; __device__ __forceinline__ unsigned cvt_pk_bf16(float lo, float hi) { unsigned r; asm volatile("v_cvt_pk_bf16_f32 %0, %1, %2" : "=v"(r) : "v"(lo), "v"(hi)); return r; }
; __device__ __forceinline__ void pmat_phase(const Frame& F, const bf16_t* Q, const bf16_t* K, bf16_t* PB, int half) {
;     ...
;         for (int jt = 0; jt < 8; ++jt) { f32x4 st = {0.f, 0.f, 0.f, 0.f};
; #pragma unroll
;             for (int ks = 0; ks < 8; ++ks) { const bf16x8 Kf = *(const LAS bf16x8*)(bK + 16 * jt * PS + 64 * ks); st = __builtin_amdgcn_mfma_f32_16x16x32_bf16(Kf, Qf[ks], st, 0, 0, 0); }
; #pragma unroll
;             for (int r = 0; r < 4; ++r) { const int jj = 16 * jt + 4 * quad + r;
;                 st[r] *= __builtin_amdgcn_exp2f(jj <= i_abs ? lgf * (float)(-jj - 1) : lgb * (float)(jj - 128)); }
;             *(GAS u32x2*)(pout + 16 * jt + lpo) = (u32x2){cvt_pk_bf16(st[0], st[1]), cvt_pk_bf16(st[2], st[3])}; }
	v_mfma_f32_16x16x32_bf16 v[108:111], v[108:111], v[28:31], 0
	s_waitcnt lgkmcnt(3)
	v_mfma_f32_16x16x32_bf16 v[108:111], v[112:115], v[24:27], v[108:111]
	ds_read_b128 v[112:115], v38 offset:34112
	s_waitcnt lgkmcnt(3)
	v_mfma_f32_16x16x32_bf16 v[108:111], v[116:119], v[20:23], v[108:111]
	ds_read_b128 v[116:119], v38 offset:34176
	s_waitcnt lgkmcnt(3)
	v_mfma_f32_16x16x32_bf16 v[108:111], v[120:123], v[16:19], v[108:111]
	ds_read_b128 v[120:123], v38 offset:34240
	s_waitcnt lgkmcnt(3)
	v_mfma_f32_16x16x32_bf16 v[108:111], v[124:127], v[12:15], v[108:111]
	s_waitcnt lgkmcnt(2)
	v_mfma_f32_16x16x32_bf16 v[108:111], v[112:115], v[8:11], v[108:111]
	s_waitcnt lgkmcnt(1)
	v_mfma_f32_16x16x32_bf16 v[108:111], v[116:119], v[4:7], v[108:111]
	s_waitcnt lgkmcnt(0)
	v_mfma_f32_16x16x32_bf16 v[108:111], v[120:123], v[0:3], v[108:111]
	v_mul_f32_e32 v112, s12, v72
	v_cndmask_b32_e64 v107, v107, v112, s[64:65]
	v_exp_f32_e32 v107, v107
	v_mul_f32_e32 v112, s12, v74
	s_nop 3
	v_mul_f32_e32 v107, v107, v108
	v_mul_f32_e32 v108, s23, v73
	v_cndmask_b32_e64 v108, v108, v112, s[66:67]
	v_exp_f32_e32 v108, v108
	v_mul_f32_e32 v112, s12, v76
	v_mul_f32_e32 v108, v108, v109
	v_mul_f32_e32 v109, s23, v75
	v_cndmask_b32_e64 v109, v109, v112, s[68:69]
	v_exp_f32_e32 v109, v109
	v_mul_f32_e32 v112, s12, v78
	v_cvt_pk_bf16_f32 v108, v107, v108
	v_mul_f32_e32 v107, s23, v79
	v_mul_f32_e32 v109, v109, v110
	v_mul_f32_e32 v110, s23, v77
	v_cndmask_b32_e64 v110, v110, v112, s[70:71]
	v_exp_f32_e32 v110, v110
	s_nop 0
	v_mul_f32_e32 v110, v110, v111
	v_cvt_pk_bf16_f32 v109, v109, v110
	global_store_dwordx2 v[36:37], v[108:109], off offset:128
	ds_read_b128 v[108:111], v38 offset:42240
	ds_read_b128 v[112:115], v38 offset:42304
	ds_read_b128 v[116:119], v38 offset:42368
	ds_read_b128 v[120:123], v38 offset:42432
	ds_read_b128 v[124:127], v38 offset:42496
	s_waitcnt lgkmcnt(4)
	v_mfma_f32_16x16x32_bf16 v[108:111], v[108:111], v[28:31], 0
	s_waitcnt lgkmcnt(3)
	v_mfma_f32_16x16x32_bf16 v[108:111], v[112:115], v[24:27], v[108:111]
	ds_read_b128 v[112:115], v38 offset:42560
	s_waitcnt lgkmcnt(3)
	v_mfma_f32_16x16x32_bf16 v[108:111], v[116:119], v[20:23], v[108:111]
	ds_read_b128 v[116:119], v38 offset:42624
	s_waitcnt lgkmcnt(3)
	v_mfma_f32_16x16x32_bf16 v[108:111], v[120:123], v[16:19], v[108:111]
	ds_read_b128 v[120:123], v38 offset:42688
	s_waitcnt lgkmcnt(3)
	v_mfma_f32_16x16x32_bf16 v[108:111], v[124:127], v[12:15], v[108:111]
	s_waitcnt lgkmcnt(2)
	v_mfma_f32_16x16x32_bf16 v[108:111], v[112:115], v[8:11], v[108:111]
	s_waitcnt lgkmcnt(1)
	v_mfma_f32_16x16x32_bf16 v[108:111], v[116:119], v[4:7], v[108:111]
	s_waitcnt lgkmcnt(0)
	v_mfma_f32_16x16x32_bf16 v[108:111], v[120:123], v[0:3], v[108:111]
	v_mul_f32_e32 v112, s12, v80
	v_cndmask_b32_e64 v107, v107, v112, s[72:73]
	v_exp_f32_e32 v107, v107
	v_mul_f32_e32 v112, s12, v82
	s_nop 3
	v_mul_f32_e32 v107, v107, v108
	v_mul_f32_e32 v108, s23, v81
	v_cndmask_b32_e64 v108, v108, v112, s[74:75]
	v_exp_f32_e32 v108, v108
	v_mul_f32_e32 v112, s12, v84
	v_mul_f32_e32 v108, v108, v109
	v_mul_f32_e32 v109, s23, v83
	v_cndmask_b32_e64 v109, v109, v112, s[76:77]
	v_exp_f32_e32 v109, v109
	v_mul_f32_e32 v112, s12, v86
	v_cvt_pk_bf16_f32 v108, v107, v108
	v_mul_f32_e32 v107, s23, v87
	v_mul_f32_e32 v109, v109, v110
	v_mul_f32_e32 v110, s23, v85
	v_cndmask_b32_e64 v110, v110, v112, s[78:79]
	v_exp_f32_e32 v110, v110
	s_nop 0
	v_mul_f32_e32 v110, v110, v111
	v_cvt_pk_bf16_f32 v109, v109, v110
	global_store_dwordx2 v[36:37], v[108:109], off offset:160
	ds_read_b128 v[108:111], v38 offset:50688
	ds_read_b128 v[112:115], v38 offset:50752
	ds_read_b128 v[116:119], v38 offset:50816
	ds_read_b128 v[120:123], v38 offset:50880
	ds_read_b128 v[124:127], v38 offset:50944
	s_waitcnt lgkmcnt(4)
; #define GAS __attribute__((address_space(1)))
; #define LAS __attribute__((address_space(3)))
; __device__ __forceinline__ unsigned cvt_pk_bf16(float lo, float hi) { unsigned r; asm volatile("v_cvt_pk_bf16_f32 %0, %1, %2" : "=v"(r) : "v"(lo), "v"(hi)); return r; }
; __device__ __forceinline__ void pmat_phase(const Frame& F, const bf16_t* Q, const bf16_t* K, bf16_t* PB, int half) {
;     ...
;         for (int jt = 0; jt < 8; ++jt) { f32x4 st = {0.f, 0.f, 0.f, 0.f};
; #pragma unroll
;             for (int ks = 0; ks < 8; ++ks) { const bf16x8 Kf = *(const LAS bf16x8*)(bK + 16 * jt * PS + 64 * ks); st = __builtin_amdgcn_mfma_f32_16x16x32_bf16(Kf, Qf[ks], st, 0, 0, 0); }
; #pragma unroll
;             for (int r = 0; r < 4; ++r) { const int jj = 16 * jt + 4 * quad + r;
;                 st[r] *= __builtin_amdgcn_exp2f(jj <= i_abs ? lgf * (float)(-jj - 1) : lgb * (float)(jj - 128)); }
;             *(GAS u32x2*)(pout + 16 * jt + lpo) = (u32x2){cvt_pk_bf16(st[0], st[1]), cvt_pk_bf16(st[2], st[3])}; }
;         __syncthreads();
;     }
	v_mfma_f32_16x16x32_bf16 v[108:111], v[108:111], v[28:31], 0
	s_waitcnt lgkmcnt(3)
	v_mfma_f32_16x16x32_bf16 v[108:111], v[112:115], v[24:27], v[108:111]
	ds_read_b128 v[112:115], v38 offset:51008
	s_waitcnt lgkmcnt(3)
	v_mfma_f32_16x16x32_bf16 v[108:111], v[116:119], v[20:23], v[108:111]
	ds_read_b128 v[116:119], v38 offset:51072
	s_waitcnt lgkmcnt(3)
	v_mfma_f32_16x16x32_bf16 v[108:111], v[120:123], v[16:19], v[108:111]
	ds_read_b128 v[120:123], v38 offset:51136
	s_waitcnt lgkmcnt(3)
	v_mfma_f32_16x16x32_bf16 v[108:111], v[124:127], v[12:15], v[108:111]
	s_waitcnt lgkmcnt(2)
	v_mfma_f32_16x16x32_bf16 v[108:111], v[112:115], v[8:11], v[108:111]
	s_waitcnt lgkmcnt(1)
	v_mfma_f32_16x16x32_bf16 v[108:111], v[116:119], v[4:7], v[108:111]
	s_waitcnt lgkmcnt(0)
	v_mfma_f32_16x16x32_bf16 v[108:111], v[120:123], v[0:3], v[108:111]
	v_mul_f32_e32 v112, s12, v88
	v_cndmask_b32_e64 v107, v107, v112, s[80:81]
	v_exp_f32_e32 v107, v107
	v_mul_f32_e32 v112, s12, v90
	s_nop 3
	v_mul_f32_e32 v107, v107, v108
	v_mul_f32_e32 v108, s23, v89
	v_cndmask_b32_e64 v108, v108, v112, s[82:83]
	v_exp_f32_e32 v108, v108
	v_mul_f32_e32 v112, s12, v92
	v_mul_f32_e32 v108, v108, v109
	v_mul_f32_e32 v109, s23, v91
	v_cndmask_b32_e64 v109, v109, v112, s[84:85]
	v_exp_f32_e32 v109, v109
	v_mul_f32_e32 v112, s12, v94
	v_cvt_pk_bf16_f32 v108, v107, v108
	v_mul_f32_e32 v109, v109, v110
	v_mul_f32_e32 v110, s23, v93
	v_cndmask_b32_e64 v110, v110, v112, s[86:87]
	v_exp_f32_e32 v110, v110
	s_nop 0
	v_mul_f32_e32 v110, v110, v111
	v_cvt_pk_bf16_f32 v109, v109, v110
	global_store_dwordx2 v[36:37], v[108:109], off offset:192
	ds_read_b128 v[108:111], v38 offset:59136
	s_waitcnt lgkmcnt(0)
	v_mfma_f32_16x16x32_bf16 v[28:31], v[108:111], v[28:31], 0
	ds_read_b128 v[108:111], v38 offset:59200
	s_waitcnt lgkmcnt(0)
	v_mfma_f32_16x16x32_bf16 v[24:27], v[108:111], v[24:27], v[28:31]
	s_nop 4
	ds_read_b128 v[28:31], v38 offset:59264
	s_waitcnt lgkmcnt(0)
	v_mfma_f32_16x16x32_bf16 v[20:23], v[28:31], v[20:23], v[24:27]
	s_nop 2
	ds_read_b128 v[24:27], v38 offset:59328
	s_waitcnt lgkmcnt(0)
	v_mfma_f32_16x16x32_bf16 v[16:19], v[24:27], v[16:19], v[20:23]
	s_nop 2
	ds_read_b128 v[20:23], v38 offset:59392
	s_waitcnt lgkmcnt(0)
	v_mfma_f32_16x16x32_bf16 v[12:15], v[20:23], v[12:15], v[16:19]
	s_nop 2
	ds_read_b128 v[16:19], v38 offset:59456
	s_waitcnt lgkmcnt(0)
	v_mfma_f32_16x16x32_bf16 v[8:11], v[16:19], v[8:11], v[12:15]
	s_nop 2
	ds_read_b128 v[12:15], v38 offset:59520
	s_waitcnt lgkmcnt(0)
	v_mfma_f32_16x16x32_bf16 v[4:7], v[12:15], v[4:7], v[8:11]
	s_nop 2
	ds_read_b128 v[8:11], v38 offset:59584
	s_waitcnt lgkmcnt(0)
	v_mfma_f32_16x16x32_bf16 v[0:3], v[8:11], v[0:3], v[4:7]
	s_nop 2
	v_mul_f32_e32 v4, s23, v95
	v_mul_f32_e32 v5, s12, v96
	v_cndmask_b32_e64 v4, v4, v5, s[88:89]
	v_exp_f32_e32 v4, v4
	v_mul_f32_e32 v5, s12, v98
	v_mul_f32_e32 v0, v4, v0
	v_mul_f32_e32 v4, s23, v97
	v_cndmask_b32_e64 v4, v4, v5, s[90:91]
	v_exp_f32_e32 v4, v4
	v_mul_f32_e32 v5, s12, v100
	v_mul_f32_e32 v1, v4, v1
	v_mul_f32_e32 v4, s23, v99
	v_cndmask_b32_e64 v4, v4, v5, s[92:93]
	v_exp_f32_e32 v4, v4
	v_mul_f32_e32 v5, s12, v102
	v_cvt_pk_bf16_f32 v0, v0, v1
	v_mul_f32_e32 v2, v4, v2
	v_mul_f32_e32 v4, s23, v101
	v_cndmask_b32_e64 v4, v4, v5, s[94:95]
	v_exp_f32_e32 v4, v4
	s_nop 0
	v_mul_f32_e32 v3, v4, v3
	v_cvt_pk_bf16_f32 v1, v2, v3
	global_store_dwordx2 v[36:37], v[0:1], off offset:224
	v_lshl_add_u64 v[36:37], v[36:37], 0, s[30:31]
	s_barrier
	s_cbranch_scc1 .LBB0_915
	v_readlane_b32 s94, v255, 49
	s_mov_b32 s93, 0x10000
	v_readlane_b32 s95, v255, 50

; #define GAS __attribute__((address_space(1)))
; __device__ __forceinline__ unsigned char* arg_ws(const Frame& F) { return (unsigned char*)arg_in(F, AW_WS / 2); }
; __device__ __forceinline__ void norm_phase(const Frame& F, const float* g) {
;     unsigned char* ws = arg_ws(F); const bf16_t* H = (const bf16_t*)(ws + WS_H); bf16_t* A = (bf16_t*)(ws + WS_A);
;     for (int r0 = F.gw; r0 < MT; r0 += 2 * F.NGW) {
;         u32x4 w[2][4];
; #pragma unroll
;         for (int k = 0; k < 2; ++k) { const int r = r0 + k * F.NGW; if (r < MT) { const GAS u32x4* hp = (const GAS u32x4*)(H + (size_t)r * D) + F.lane;
; #pragma unroll
;             for (int j = 0; j < 4; ++j) w[k][j] = hp[64 * j]; } }
.LBB0_1283:
	v_readlane_b32 s0, v254, 3
	v_readlane_b32 s1, v254, 4
	s_cmp_ge_i32 s60, s0
	s_cselect_b64 s[22:23], -1, 0
	s_cmp_lt_i32 s60, s1
	s_cselect_b64 s[0:1], -1, 0
	s_and_b64 s[0:1], s[22:23], s[0:1]
	s_andn2_b64 vcc, exec, s[0:1]
	s_cbranch_vccnz .LBB0_1291
	s_mov_b32 s0, -1
	v_readlane_b32 s1, v254, 2
	v_mbcnt_lo_u32_b32 v0, s0, 0
	v_mbcnt_hi_u32_b32 v0, s0, v0
	v_readlane_b32 s0, v254, 5
	v_mov_b32_e32 v1, v193
	s_nop 0
	v_add_u32_e32 v0, s0, v0
	s_lshl_b32 s1, s1, 3
	v_readfirstlane_b32 s0, v0
	s_ashr_i32 s0, s0, 6
	s_add_i32 s28, s1, s0
	s_add_i32 s0, 0, 0x23b00
	s_cmp_gt_i32 s28, 0x105ff
	v_add_u32_e32 v2, s0, v1
	ds_read_b32 v4, v2 offset:32
	ds_read_b32 v2, v2 offset:36
	v_add_u32_e32 v1, 0, v1
	v_add_u32_e32 v3, 0x23ba8, v1
	v_add_u32_e32 v1, 0x23bac, v1
	s_waitcnt lgkmcnt(0)
	v_readfirstlane_b32 s10, v4
	v_readfirstlane_b32 s11, v2
	ds_read_b32 v2, v3
	ds_read_b32 v1, v1
	s_waitcnt lgkmcnt(0)
	v_readfirstlane_b32 s0, v2
	v_readfirstlane_b32 s1, v1
	s_cbranch_scc1 .LBB0_1291
	v_readlane_b32 s12, v255, 37
	v_readlane_b32 s13, v255, 38
	s_lshl_b32 s18, s12, 11
	v_and_b32_e32 v2, 63, v0
	s_lshl_b64 s[12:13], s[18:19], 2
	v_lshlrev_b32_e32 v192, 4, v2
	s_add_u32 s10, s10, s12
	v_lshl_add_u64 v[0:1], s[0:1], 0, v[192:193]
	s_mov_b64 s[0:1], 0xd00000
	s_addc_u32 s11, s11, s13
	v_lshl_add_u64 v[32:33], v[0:1], 0, s[0:1]
	s_mov_b64 s[0:1], 0x11300000
	v_lshlrev_b32_e32 v192, 5, v2
	v_lshl_add_u64 v[34:35], v[0:1], 0, s[0:1]
	v_lshl_add_u64 v[36:37], s[10:11], 0, v[192:193]
	s_mov_b64 s[0:1], 0x1000
	v_lshl_add_u64 v[38:39], v[36:37], 0, s[0:1]
	s_mov_b64 s[0:1], 0x1800
	v_lshl_add_u64 v[40:41], v[36:37], 0, s[0:1]
	s_mov_b32 s12, 0xf800000
	global_load_dwordx4 v[128:131], v[36:37], off offset:16
	global_load_dwordx4 v[132:135], v[36:37], off
	global_load_dwordx4 v[136:139], v[36:37], off offset:2064
	global_load_dwordx4 v[140:143], v[36:37], off offset:2048
	global_load_dwordx4 v[144:147], v[38:39], off offset:16
	global_load_dwordx4 v[148:151], v[38:39], off
	global_load_dwordx4 v[152:155], v[40:41], off offset:16
	global_load_dwordx4 v[156:159], v[40:41], off
	s_branch .LBB0_1287

; #define GAS __attribute__((address_space(1)))
; __device__ __forceinline__ unsigned cvt_pk_bf16(float lo, float hi) { unsigned r; asm volatile("v_cvt_pk_bf16_f32 %0, %1, %2" : "=v"(r) : "v"(lo), "v"(hi)); return r; }
; __device__ __forceinline__ float bf_lo(unsigned w) { return __uint_as_float(w << 16); }
; __device__ __forceinline__ float bf_hi(unsigned w) { return __uint_as_float(w & 0xffff0000u); }
; __device__ __forceinline__ void norm_phase(const Frame& F, const float* g) {
;     ...
; #pragma unroll
;         for (int k = 0; k < 2; ++k) { const int r = r0 + k * F.NGW; if (r < MT) { GAS u32x4* ap = (GAS u32x4*)(A + (size_t)r * D) + F.lane; float ss = 0.f;
; #pragma unroll
;             for (int j = 0; j < 4; ++j)
; #pragma unroll
;                 for (int e = 0; e < 4; ++e) { const float x = bf_lo(w[k][j][e]), y = bf_hi(w[k][j][e]); ss += x * x + y * y; }
;             const float rstd = 1.0f / sqrtf(wave_sum(ss) * (1.f / D) + NORM_EPS);
; #pragma unroll
;             for (int j = 0; j < 4; ++j) { const f32x4 g0 = *((const GAS f32x4*)g + 2 * (F.lane + 64 * j)), g1 = *((const GAS f32x4*)g + 2 * (F.lane + 64 * j) + 1); u32x4 o;
;                 o.x = cvt_pk_bf16(bf_lo(w[k][j].x) * rstd * g0[0], bf_hi(w[k][j].x) * rstd * g0[1]); o.y = cvt_pk_bf16(bf_lo(w[k][j].y) * rstd * g0[2], bf_hi(w[k][j].y) * rstd * g0[3]);
;                 o.z = cvt_pk_bf16(bf_lo(w[k][j].z) * rstd * g1[0], bf_hi(w[k][j].z) * rstd * g1[1]); o.w = cvt_pk_bf16(bf_lo(w[k][j].w) * rstd * g1[2], bf_hi(w[k][j].w) * rstd * g1[3]);
;                 ap[64 * j] = o; } } }
.LBB0_1289:
	s_waitcnt vmcnt(0)
	v_and_b32_e32 v57, 0xffff0000, v28
	v_and_b32_e32 v58, 0xffff0000, v29
	v_lshlrev_b32_e32 v59, 16, v28
	v_mul_f32_e32 v28, v57, v57
	v_lshlrev_b32_e32 v60, 16, v29
	v_mul_f32_e32 v29, v58, v58
	v_fmac_f32_e32 v28, v59, v59
	v_fmac_f32_e32 v29, v60, v60
	v_and_b32_e32 v61, 0xffff0000, v30
	v_add_f32_e32 v28, v28, v29
	v_lshlrev_b32_e32 v62, 16, v30
	v_mul_f32_e32 v29, v61, v61
	v_fmac_f32_e32 v29, v62, v62
	v_and_b32_e32 v63, 0xffff0000, v31
	v_add_f32_e32 v28, v29, v28
	v_lshlrev_b32_e32 v64, 16, v31
	v_mul_f32_e32 v29, v63, v63
	v_and_b32_e32 v55, 0xffff0000, v24
	v_fmac_f32_e32 v29, v64, v64
	v_lshlrev_b32_e32 v56, 16, v24
	v_mul_f32_e32 v24, v55, v55
	v_and_b32_e32 v53, 0xffff0000, v25
	v_add_f32_e32 v28, v29, v28
	v_fmac_f32_e32 v24, v56, v56
	v_lshlrev_b32_e32 v54, 16, v25
	v_mul_f32_e32 v25, v53, v53
	v_add_f32_e32 v24, v24, v28
	v_fmac_f32_e32 v25, v54, v54
	v_and_b32_e32 v51, 0xffff0000, v26
	v_add_f32_e32 v24, v25, v24
	v_lshlrev_b32_e32 v52, 16, v26
	v_mul_f32_e32 v25, v51, v51
	v_fmac_f32_e32 v25, v52, v52
	v_and_b32_e32 v49, 0xffff0000, v27
	v_add_f32_e32 v24, v25, v24
	v_lshlrev_b32_e32 v50, 16, v27
	v_mul_f32_e32 v25, v49, v49
	v_and_b32_e32 v47, 0xffff0000, v20
	v_fmac_f32_e32 v25, v50, v50
	v_lshlrev_b32_e32 v48, 16, v20
	v_mul_f32_e32 v20, v47, v47
	v_and_b32_e32 v45, 0xffff0000, v21
	v_add_f32_e32 v24, v25, v24
	v_fmac_f32_e32 v20, v48, v48
	v_lshlrev_b32_e32 v46, 16, v21
	v_mul_f32_e32 v21, v45, v45
	v_add_f32_e32 v20, v20, v24
	v_fmac_f32_e32 v21, v46, v46
	v_and_b32_e32 v43, 0xffff0000, v22
	v_add_f32_e32 v20, v21, v20
	v_lshlrev_b32_e32 v44, 16, v22
	v_mul_f32_e32 v21, v43, v43
	v_fmac_f32_e32 v21, v44, v44
	v_and_b32_e32 v31, 0xffff0000, v23
	v_add_f32_e32 v20, v21, v20
	v_lshlrev_b32_e32 v42, 16, v23
	v_mul_f32_e32 v21, v31, v31
	v_and_b32_e32 v22, 0xffff0000, v16
	v_fmac_f32_e32 v21, v42, v42
	v_lshlrev_b32_e32 v23, 16, v16
	v_mul_f32_e32 v16, v22, v22
	v_and_b32_e32 v24, 0xffff0000, v17
	v_add_f32_e32 v20, v21, v20
	v_fmac_f32_e32 v16, v23, v23
	v_lshlrev_b32_e32 v25, 16, v17
	v_mul_f32_e32 v17, v24, v24
	v_add_f32_e32 v16, v16, v20
	v_fmac_f32_e32 v17, v25, v25
	v_and_b32_e32 v26, 0xffff0000, v18
	v_add_f32_e32 v16, v17, v16
	v_lshlrev_b32_e32 v28, 16, v18
	v_mul_f32_e32 v17, v26, v26
	v_fmac_f32_e32 v17, v28, v28
	v_and_b32_e32 v27, 0xffff0000, v19
	v_add_f32_e32 v16, v17, v16
	v_lshlrev_b32_e32 v29, 16, v19
	v_mul_f32_e32 v17, v27, v27
	v_fmac_f32_e32 v17, v29, v29
	v_add_f32_e32 v16, v17, v16
	ds_swizzle_b32 v17, v16 offset:swizzle(SWAP,1)
	v_lshl_add_u64 v[20:21], v[34:35], 0, s[0:1]
	s_waitcnt lgkmcnt(0)
	v_add_f32_e32 v16, v16, v17
	ds_swizzle_b32 v17, v16 offset:swizzle(SWAP,2)
	s_waitcnt lgkmcnt(0)
	v_add_f32_e32 v16, v16, v17
	ds_swizzle_b32 v17, v16 offset:swizzle(SWAP,4)
	s_waitcnt lgkmcnt(0)
	v_add_f32_e32 v16, v16, v17
	ds_swizzle_b32 v17, v16 offset:swizzle(SWAP,8)
	s_waitcnt lgkmcnt(0)
	v_add_f32_e32 v16, v16, v17
	ds_swizzle_b32 v17, v16 offset:swizzle(SWAP,16)
	s_waitcnt lgkmcnt(0)
	v_add_f32_e32 v16, v16, v17
	v_mov_b32_e32 v17, v16
	s_nop 1
	v_permlane32_swap_b32_e32 v16, v17
	v_add_f32_e32 v16, v16, v17
	v_fmamk_f32 v16, v16, 0x3a000000, v250
	v_cmp_gt_f32_e32 vcc, s12, v16
	v_mul_f32_e32 v17, 0x4f800000, v16
	s_nop 0
	v_cndmask_b32_e32 v16, v16, v17, vcc
	v_sqrt_f32_e32 v17, v16
	s_nop 0
	v_add_u32_e32 v18, -1, v17
	v_fma_f32 v19, -v18, v17, v16
	v_cmp_ge_f32_e64 s[0:1], 0, v19
	v_add_u32_e32 v19, 1, v17
	s_nop 0
	v_cndmask_b32_e64 v18, v17, v18, s[0:1]
	v_fma_f32 v17, -v19, v17, v16
	v_cmp_lt_f32_e64 s[0:1], 0, v17
	s_nop 1
	v_cndmask_b32_e64 v17, v18, v19, s[0:1]
	v_mul_f32_e32 v18, 0x37800000, v17
	v_cndmask_b32_e32 v17, v17, v18, vcc
	v_cmp_class_f32_e32 vcc, v16, v251
	s_nop 1
	v_cndmask_b32_e32 v16, v17, v16, vcc
	v_div_scale_f32 v17, s[0:1], v16, v16, 1.0
	v_rcp_f32_e32 v18, v17
	s_nop 0
	v_fma_f32 v19, -v17, v18, 1.0
	v_fmac_f32_e32 v18, v19, v18
	v_div_scale_f32 v19, vcc, 1.0, v16, 1.0
	v_mul_f32_e32 v30, v19, v18
	v_fma_f32 v65, -v17, v30, v19
	v_fmac_f32_e32 v30, v65, v18
	v_fma_f32 v17, -v17, v30, v19
	v_div_fmas_f32 v17, v17, v18, v30
	v_div_fixup_f32 v30, v17, v16, 1.0
	v_mul_f32_e32 v57, v30, v57
	v_mul_f32_e32 v59, v30, v59
	v_mul_f32_e32 v58, v30, v58
	v_mul_f32_e32 v56, v30, v56
	v_mul_f32_e32 v52, v30, v52
	v_mul_f32_e32 v51, v30, v51
	v_mul_f32_e32 v55, v30, v55
	v_mul_f32_e32 v54, v30, v54
	v_mul_f32_e32 v53, v30, v53
	v_mul_f32_e32 v48, v30, v48
	v_mul_f32_e32 v44, v30, v44
	v_mul_f32_e32 v43, v30, v43
	v_mul_f32_e32 v47, v30, v47
	v_mul_f32_e32 v46, v30, v46
	v_mul_f32_e32 v45, v30, v45
	v_mul_f32_e32 v23, v30, v23
	v_mul_f32_e32 v22, v30, v22
	v_mul_f32_e32 v24, v30, v24
	s_andn2_b64 vcc, exec, s[30:31]
	v_mul_f32_e32 v57, v133, v57
	v_mul_f32_e32 v59, v132, v59
	v_cvt_pk_bf16_f32 v66, v59, v57
	v_mul_f32_e32 v57, v30, v60
	v_mul_f32_e32 v57, v134, v57
	v_mul_f32_e32 v58, v135, v58
	v_cvt_pk_bf16_f32 v67, v57, v58
	v_mul_f32_e32 v57, v30, v62
	v_mul_f32_e32 v16, v128, v57
	v_mul_f32_e32 v57, v30, v61
	v_mul_f32_e32 v17, v129, v57
	v_cvt_pk_bf16_f32 v68, v16, v17
	v_mul_f32_e32 v16, v30, v64
	v_mul_f32_e32 v17, v30, v63
	v_mul_f32_e32 v16, v130, v16
	v_mul_f32_e32 v17, v131, v17
	v_cvt_pk_bf16_f32 v69, v16, v17
	global_store_dwordx4 v[20:21], v[66:69], off
	v_mul_f32_e32 v16, v52, v136
	v_mul_f32_e32 v56, v56, v140
	v_mul_f32_e32 v17, v51, v137
	v_mul_f32_e32 v55, v55, v141
	v_cvt_pk_bf16_f32 v56, v56, v55
	v_mul_f32_e32 v54, v54, v142
	v_mul_f32_e32 v53, v53, v143
	v_cvt_pk_bf16_f32 v57, v54, v53
	v_cvt_pk_bf16_f32 v58, v16, v17
	v_mul_f32_e32 v16, v30, v50
	v_mul_f32_e32 v17, v30, v49
	v_mul_f32_e32 v16, v16, v138
	v_mul_f32_e32 v17, v17, v139
	v_cvt_pk_bf16_f32 v59, v16, v17
	global_store_dwordx4 v[20:21], v[56:59], off offset:1024
	v_mul_f32_e32 v16, v44, v144
	v_mul_f32_e32 v48, v48, v148
	v_mul_f32_e32 v17, v43, v145
	v_mul_f32_e32 v47, v47, v149
	v_cvt_pk_bf16_f32 v48, v48, v47
	v_mul_f32_e32 v46, v46, v150
	v_mul_f32_e32 v45, v45, v151
	v_cvt_pk_bf16_f32 v49, v46, v45
	v_cvt_pk_bf16_f32 v50, v16, v17
	v_mul_f32_e32 v16, v30, v42
	v_mul_f32_e32 v17, v30, v31
	v_mul_f32_e32 v16, v16, v146
	v_mul_f32_e32 v17, v17, v147
	v_cvt_pk_bf16_f32 v51, v16, v17
	global_store_dwordx4 v[20:21], v[48:51], off offset:2048
	v_mul_f32_e32 v23, v23, v156
	v_mul_f32_e32 v22, v22, v157
	v_cvt_pk_bf16_f32 v22, v23, v22
	v_mul_f32_e32 v23, v30, v25
	v_mul_f32_e32 v23, v23, v158
	v_mul_f32_e32 v24, v24, v159
	v_cvt_pk_bf16_f32 v23, v23, v24
	v_mul_f32_e32 v24, v30, v28
	v_mul_f32_e32 v16, v24, v152
	v_mul_f32_e32 v24, v30, v26
	v_mul_f32_e32 v17, v24, v153
	v_cvt_pk_bf16_f32 v24, v16, v17
	v_mul_f32_e32 v16, v30, v29
	v_mul_f32_e32 v17, v30, v27
	v_mul_f32_e32 v16, v16, v154
	v_mul_f32_e32 v17, v17, v155
	v_cvt_pk_bf16_f32 v25, v16, v17
	global_store_dwordx4 v[20:21], v[22:25], off offset:3072
	s_cbranch_vccnz .LBB0_1286
; #define GAS __attribute__((address_space(1)))
; __device__ __forceinline__ unsigned cvt_pk_bf16(float lo, float hi) { unsigned r; asm volatile("v_cvt_pk_bf16_f32 %0, %1, %2" : "=v"(r) : "v"(lo), "v"(hi)); return r; }
; __device__ __forceinline__ float bf_lo(unsigned w) { return __uint_as_float(w << 16); }
; __device__ __forceinline__ float bf_hi(unsigned w) { return __uint_as_float(w & 0xffff0000u); }
; __device__ __forceinline__ void norm_phase(const Frame& F, const float* g) {
;     ...
; #pragma unroll
;         for (int k = 0; k < 2; ++k) { const int r = r0 + k * F.NGW; if (r < MT) { GAS u32x4* ap = (GAS u32x4*)(A + (size_t)r * D) + F.lane; float ss = 0.f;
; #pragma unroll
;             for (int j = 0; j < 4; ++j)
; #pragma unroll
;                 for (int e = 0; e < 4; ++e) { const float x = bf_lo(w[k][j][e]), y = bf_hi(w[k][j][e]); ss += x * x + y * y; }
;             const float rstd = 1.0f / sqrtf(wave_sum(ss) * (1.f / D) + NORM_EPS);
; #pragma unroll
;             for (int j = 0; j < 4; ++j) { const f32x4 g0 = *((const GAS f32x4*)g + 2 * (F.lane + 64 * j)), g1 = *((const GAS f32x4*)g + 2 * (F.lane + 64 * j) + 1); u32x4 o;
;                 o.x = cvt_pk_bf16(bf_lo(w[k][j].x) * rstd * g0[0], bf_hi(w[k][j].x) * rstd * g0[1]); o.y = cvt_pk_bf16(bf_lo(w[k][j].y) * rstd * g0[2], bf_hi(w[k][j].y) * rstd * g0[3]);
;                 o.z = cvt_pk_bf16(bf_lo(w[k][j].z) * rstd * g1[0], bf_hi(w[k][j].z) * rstd * g1[1]); o.w = cvt_pk_bf16(bf_lo(w[k][j].w) * rstd * g1[2], bf_hi(w[k][j].w) * rstd * g1[3]);
;                 ap[64 * j] = o; } } }
	v_and_b32_e32 v57, 0xffff0000, v12
	v_and_b32_e32 v58, 0xffff0000, v13
	v_lshlrev_b32_e32 v59, 16, v12
	v_mul_f32_e32 v16, v57, v57
	v_lshlrev_b32_e32 v60, 16, v13
	v_mul_f32_e32 v17, v58, v58
	v_fmac_f32_e32 v16, v59, v59
	v_fmac_f32_e32 v17, v60, v60
	v_and_b32_e32 v61, 0xffff0000, v14
	v_add_f32_e32 v16, v16, v17
	v_lshlrev_b32_e32 v62, 16, v14
	v_mul_f32_e32 v17, v61, v61
	v_fmac_f32_e32 v17, v62, v62
	v_and_b32_e32 v63, 0xffff0000, v15
	v_add_f32_e32 v16, v17, v16
	v_lshlrev_b32_e32 v64, 16, v15
	v_mul_f32_e32 v17, v63, v63
	v_fmac_f32_e32 v17, v64, v64
	v_and_b32_e32 v55, 0xffff0000, v8
	v_add_f32_e32 v16, v17, v16
	v_lshlrev_b32_e32 v56, 16, v8
	v_mul_f32_e32 v17, v55, v55
	v_fmac_f32_e32 v17, v56, v56
	v_and_b32_e32 v53, 0xffff0000, v9
	v_add_f32_e32 v16, v17, v16
	v_lshlrev_b32_e32 v54, 16, v9
	v_mul_f32_e32 v17, v53, v53
	v_fmac_f32_e32 v17, v54, v54
	v_and_b32_e32 v51, 0xffff0000, v10
	v_add_f32_e32 v16, v17, v16
	v_lshlrev_b32_e32 v52, 16, v10
	v_mul_f32_e32 v17, v51, v51
	v_fmac_f32_e32 v17, v52, v52
	v_and_b32_e32 v49, 0xffff0000, v11
	v_add_f32_e32 v16, v17, v16
	v_lshlrev_b32_e32 v50, 16, v11
	v_mul_f32_e32 v17, v49, v49
	v_fmac_f32_e32 v17, v50, v50
	v_and_b32_e32 v47, 0xffff0000, v4
	v_add_f32_e32 v16, v17, v16
	v_lshlrev_b32_e32 v48, 16, v4
	v_mul_f32_e32 v17, v47, v47
	v_fmac_f32_e32 v17, v48, v48
	v_and_b32_e32 v45, 0xffff0000, v5
	v_add_f32_e32 v16, v17, v16
	v_lshlrev_b32_e32 v46, 16, v5
	v_mul_f32_e32 v17, v45, v45
	v_fmac_f32_e32 v17, v46, v46
	v_and_b32_e32 v43, 0xffff0000, v6
	v_add_f32_e32 v16, v17, v16
	v_lshlrev_b32_e32 v44, 16, v6
	v_mul_f32_e32 v17, v43, v43
	v_fmac_f32_e32 v17, v44, v44
	v_and_b32_e32 v31, 0xffff0000, v7
	v_add_f32_e32 v16, v17, v16
	v_lshlrev_b32_e32 v42, 16, v7
	v_mul_f32_e32 v17, v31, v31
	v_fmac_f32_e32 v17, v42, v42
	v_and_b32_e32 v28, 0xffff0000, v0
	v_add_f32_e32 v16, v17, v16
	v_lshlrev_b32_e32 v29, 16, v0
	v_mul_f32_e32 v17, v28, v28
	v_fmac_f32_e32 v17, v29, v29
	v_and_b32_e32 v26, 0xffff0000, v1
	v_add_f32_e32 v16, v17, v16
	v_lshlrev_b32_e32 v27, 16, v1
	v_mul_f32_e32 v17, v26, v26
	v_fmac_f32_e32 v17, v27, v27
	v_and_b32_e32 v24, 0xffff0000, v2
	v_add_f32_e32 v16, v17, v16
	v_lshlrev_b32_e32 v25, 16, v2
	v_mul_f32_e32 v17, v24, v24
	v_fmac_f32_e32 v17, v25, v25
	v_and_b32_e32 v22, 0xffff0000, v3
	v_add_f32_e32 v16, v17, v16
	v_lshlrev_b32_e32 v23, 16, v3
	v_mul_f32_e32 v17, v22, v22
	v_fmac_f32_e32 v17, v23, v23
	v_add_f32_e32 v16, v17, v16
	ds_swizzle_b32 v17, v16 offset:swizzle(SWAP,1)
	s_ashr_i32 s29, s28, 31
	s_lshl_b64 s[0:1], s[28:29], 12
	v_lshl_add_u64 v[20:21], v[34:35], 0, s[0:1]
	s_waitcnt lgkmcnt(0)
	v_add_f32_e32 v16, v16, v17
	ds_swizzle_b32 v17, v16 offset:swizzle(SWAP,2)
	s_waitcnt lgkmcnt(0)
	v_add_f32_e32 v16, v16, v17
	ds_swizzle_b32 v17, v16 offset:swizzle(SWAP,4)
	s_waitcnt lgkmcnt(0)
	v_add_f32_e32 v16, v16, v17
	ds_swizzle_b32 v17, v16 offset:swizzle(SWAP,8)
	s_waitcnt lgkmcnt(0)
	v_add_f32_e32 v16, v16, v17
	ds_swizzle_b32 v17, v16 offset:swizzle(SWAP,16)
	s_waitcnt lgkmcnt(0)
	v_add_f32_e32 v16, v16, v17
	v_mov_b32_e32 v17, v16
	s_nop 1
	v_permlane32_swap_b32_e32 v16, v17
	v_add_f32_e32 v16, v16, v17
	v_fmamk_f32 v16, v16, 0x3a000000, v250
	v_cmp_gt_f32_e32 vcc, s12, v16
	v_mul_f32_e32 v17, 0x4f800000, v16
	s_nop 0
	v_cndmask_b32_e32 v16, v16, v17, vcc
	v_sqrt_f32_e32 v17, v16
	s_nop 0
	v_add_u32_e32 v18, -1, v17
	v_fma_f32 v19, -v18, v17, v16
	v_cmp_ge_f32_e64 s[0:1], 0, v19
	v_add_u32_e32 v19, 1, v17
	s_nop 0
	v_cndmask_b32_e64 v18, v17, v18, s[0:1]
	v_fma_f32 v17, -v19, v17, v16
	v_cmp_lt_f32_e64 s[0:1], 0, v17
	s_nop 1
	v_cndmask_b32_e64 v17, v18, v19, s[0:1]
	v_mul_f32_e32 v18, 0x37800000, v17
	v_cndmask_b32_e32 v17, v17, v18, vcc
	v_cmp_class_f32_e32 vcc, v16, v251
	s_nop 1
	v_cndmask_b32_e32 v16, v17, v16, vcc
	v_div_scale_f32 v17, s[0:1], v16, v16, 1.0
	v_rcp_f32_e32 v18, v17
	s_nop 0
	v_fma_f32 v19, -v17, v18, 1.0
	v_fmac_f32_e32 v18, v19, v18
	v_div_scale_f32 v19, vcc, 1.0, v16, 1.0
	v_mul_f32_e32 v30, v19, v18
	v_fma_f32 v65, -v17, v30, v19
	v_fmac_f32_e32 v30, v65, v18
	v_fma_f32 v17, -v17, v30, v19
	v_div_fmas_f32 v17, v17, v18, v30
	v_div_fixup_f32 v30, v17, v16, 1.0
	v_mul_f32_e32 v57, v30, v57
	v_mul_f32_e32 v59, v30, v59
	v_mul_f32_e32 v58, v30, v58
	v_mul_f32_e32 v56, v30, v56
	v_mul_f32_e32 v52, v30, v52
	v_mul_f32_e32 v51, v30, v51
	v_mul_f32_e32 v55, v30, v55
	v_mul_f32_e32 v54, v30, v54
	v_mul_f32_e32 v53, v30, v53
	v_mul_f32_e32 v48, v30, v48
	v_mul_f32_e32 v44, v30, v44
	v_mul_f32_e32 v43, v30, v43
	v_mul_f32_e32 v47, v30, v47
	v_mul_f32_e32 v46, v30, v46
	v_mul_f32_e32 v45, v30, v45
	v_mul_f32_e32 v25, v30, v25
	v_mul_f32_e32 v24, v30, v24
	v_mul_f32_e32 v29, v30, v29
	v_mul_f32_e32 v28, v30, v28
	v_mul_f32_e32 v27, v30, v27
	v_mul_f32_e32 v26, v30, v26
	v_mul_f32_e32 v57, v133, v57
	v_mul_f32_e32 v59, v132, v59
	v_cvt_pk_bf16_f32 v66, v59, v57
	v_mul_f32_e32 v57, v30, v60
	v_mul_f32_e32 v57, v134, v57
	v_mul_f32_e32 v58, v135, v58
	v_cvt_pk_bf16_f32 v67, v57, v58
	v_mul_f32_e32 v57, v30, v62
	v_mul_f32_e32 v16, v128, v57
	v_mul_f32_e32 v57, v30, v61
	v_mul_f32_e32 v17, v129, v57
	v_cvt_pk_bf16_f32 v68, v16, v17
	v_mul_f32_e32 v16, v30, v64
	v_mul_f32_e32 v17, v30, v63
	v_mul_f32_e32 v16, v130, v16
	v_mul_f32_e32 v17, v131, v17
	v_cvt_pk_bf16_f32 v69, v16, v17
	global_store_dwordx4 v[20:21], v[66:69], off
	v_mul_f32_e32 v16, v52, v136
	v_mul_f32_e32 v56, v56, v140
	v_mul_f32_e32 v17, v51, v137
	v_mul_f32_e32 v55, v55, v141
	v_cvt_pk_bf16_f32 v56, v56, v55
	v_mul_f32_e32 v54, v54, v142
	v_mul_f32_e32 v53, v53, v143
	v_cvt_pk_bf16_f32 v57, v54, v53
	v_cvt_pk_bf16_f32 v58, v16, v17
	v_mul_f32_e32 v16, v30, v50
	v_mul_f32_e32 v17, v30, v49
	v_mul_f32_e32 v16, v16, v138
	v_mul_f32_e32 v17, v17, v139
	v_cvt_pk_bf16_f32 v59, v16, v17
	global_store_dwordx4 v[20:21], v[56:59], off offset:1024
	v_mul_f32_e32 v16, v44, v144
	v_mul_f32_e32 v48, v48, v148
	v_mul_f32_e32 v17, v43, v145
	v_mul_f32_e32 v47, v47, v149
	v_cvt_pk_bf16_f32 v48, v48, v47
	v_mul_f32_e32 v46, v46, v150
	v_mul_f32_e32 v45, v45, v151
	v_cvt_pk_bf16_f32 v49, v46, v45
	v_cvt_pk_bf16_f32 v50, v16, v17
	v_mul_f32_e32 v16, v30, v42
	v_mul_f32_e32 v17, v30, v31
	v_mul_f32_e32 v16, v16, v146
	v_mul_f32_e32 v17, v17, v147
	v_cvt_pk_bf16_f32 v51, v16, v17
	global_store_dwordx4 v[20:21], v[48:51], off offset:2048
	v_mul_f32_e32 v16, v25, v152
	v_mul_f32_e32 v17, v24, v153
	v_mul_f32_e32 v29, v29, v156
	v_mul_f32_e32 v28, v28, v157
	v_cvt_pk_bf16_f32 v42, v29, v28
	v_mul_f32_e32 v27, v27, v158
	v_mul_f32_e32 v26, v26, v159
	v_cvt_pk_bf16_f32 v43, v27, v26
	v_cvt_pk_bf16_f32 v44, v16, v17
	v_mul_f32_e32 v16, v30, v23
	v_mul_f32_e32 v17, v30, v22
	v_mul_f32_e32 v16, v16, v154
	v_mul_f32_e32 v17, v17, v155
	v_cvt_pk_bf16_f32 v45, v16, v17
	global_store_dwordx4 v[20:21], v[42:45], off offset:3072
	s_branch .LBB0_1286

; #define GAS __attribute__((address_space(1)))
; __device__ __forceinline__ unsigned char* arg_ws(const Frame& F) { return (unsigned char*)arg_in(F, AW_WS / 2); }
; __device__ __forceinline__ unsigned char* arg_out(const Frame& F) { return (unsigned char*)arg_in(F, AW_OUT / 2); }
; __device__ __forceinline__ void final_phase(const Frame& F) {
;     const bf16_t* H = (const bf16_t*)(arg_ws(F) + WS_H); const float* g = arg_in(F, 19); float* outp = (float*)arg_out(F);
;     constexpr int NREAL = NP * SP + NS * SS;
;     for (int i = F.gw; i < NREAL; i += F.NGW) {
;         int r; if (i < NP * SP) r = (i / SP) * LP_P + PADF + NMETA + (i % SP); else { const int k = i - NP * SP; r = ROWS0 + (k / SS) * LP_S + PADF + NMETA + (k % SS); }
;         const GAS u32x4* hp = (const GAS u32x4*)(H + (size_t)r * D) + F.lane; GAS f32x4* op = (GAS f32x4*)(outp + (size_t)i * D);
;         u32x4 w[4]; float ss = 0.f;
.LBB0_1858:
	v_readlane_b32 s0, v254, 3
	v_readlane_b32 s1, v254, 4
	v_readlane_b32 s1, v255, 24
	s_cmp_ge_i32 s1, s0
	s_cselect_b64 s[2:3], -1, 0
	s_and_b64 s[0:1], s[2:3], s[22:23]
	s_and_b64 vcc, exec, s[0:1]
	s_cbranch_vccz .LBB0_1866
	s_mov_b32 s0, -1
	v_readlane_b32 s1, v254, 2
	v_mbcnt_lo_u32_b32 v0, s0, 0
	v_mbcnt_hi_u32_b32 v0, s0, v0
	v_readlane_b32 s0, v254, 5
	v_mov_b32_e32 v1, 0
	v_mov_b32_e32 v7, 0
	v_add_u32_e32 v0, s0, v0
	s_lshl_b32 s1, s1, 3
	v_add_u32_e32 v1, 0, v1
	v_add_u32_e32 v2, 0x23ba8, v1
	v_add_u32_e32 v3, 0x23bac, v1
	ds_read_b32 v2, v2
	ds_read_b32 v3, v3
	v_add_u32_e32 v4, 0x23ba0, v1
	v_readfirstlane_b32 s0, v0
	s_ashr_i32 s0, s0, 6
	s_waitcnt lgkmcnt(0)
	v_readfirstlane_b32 s20, v2
	v_readfirstlane_b32 s21, v3
	v_add_u32_e32 v2, 0x23b98, v1
	v_add_u32_e32 v3, 0x23b9c, v1
	v_add_u32_e32 v1, 0x23ba4, v1
	ds_read_b32 v2, v2
	ds_read_b32 v3, v3
	ds_read_b32 v4, v4
	ds_read_b32 v1, v1
	s_add_i32 s18, s1, s0
	s_waitcnt lgkmcnt(0)
	v_readfirstlane_b32 s0, v2
	v_readfirstlane_b32 s1, v3
	v_readfirstlane_b32 s4, v4
	s_cmp_gt_i32 s18, 0xffff
	v_readfirstlane_b32 s5, v1
	s_cbranch_scc1 .LBB0_1866
	v_and_b32_e32 v2, 63, v0
	v_lshlrev_b32_e32 v6, 4, v2
	v_lshlrev_b32_e32 v8, 1, v2
	v_lshl_add_u64 v[0:1], s[20:21], 0, v[6:7]
	v_lshlrev_b32_e32 v6, 5, v2
	v_or_b32_e32 v10, 0x100, v8
	v_lshl_add_u64 v[2:3], s[0:1], 0, v[6:7]
	v_lshlrev_b32_e32 v6, 4, v10
	v_or_b32_e32 v12, 0x180, v8
	s_mov_b64 s[6:7], 0xd00000
	v_lshl_add_u64 v[4:5], s[0:1], 0, v[6:7]
	v_lshlrev_b32_e32 v6, 4, v12
	v_lshl_add_u64 v[0:1], v[0:1], 0, s[6:7]
	v_lshl_add_u64 v[6:7], s[0:1], 0, v[6:7]
	v_lshlrev_b32_e32 v8, 4, v8
	v_lshlrev_b32_e32 v9, 4, v10
	v_lshlrev_b32_e32 v10, 4, v12
	v_mov_b32_e32 v11, 0x358637bd
	s_mov_b32 s6, 0xf800000
	v_mov_b32_e32 v12, 0x260
	global_load_dwordx4 v[128:131], v[2:3], off offset:16
	global_load_dwordx4 v[132:135], v[2:3], off
	global_load_dwordx4 v[136:139], v[2:3], off offset:2048
	global_load_dwordx4 v[140:143], v[2:3], off offset:2064
	global_load_dwordx4 v[144:147], v[4:5], off
	global_load_dwordx4 v[148:151], v[4:5], off offset:16
	global_load_dwordx4 v[152:155], v[6:7], off
	global_load_dwordx4 v[156:159], v[6:7], off offset:16
	s_branch .LBB0_1862
; #define GAS __attribute__((address_space(1)))
; __device__ __forceinline__ float bf_lo(unsigned w) { return __uint_as_float(w << 16); }
; __device__ __forceinline__ float bf_hi(unsigned w) { return __uint_as_float(w & 0xffff0000u); }
; __device__ __forceinline__ void final_phase(const Frame& F) {
;     ...
;     for (int i = F.gw; i < NREAL; i += F.NGW) {
;         int r; if (i < NP * SP) r = (i / SP) * LP_P + PADF + NMETA + (i % SP); else { const int k = i - NP * SP; r = ROWS0 + (k / SS) * LP_S + PADF + NMETA + (k % SS); }
;         const GAS u32x4* hp = (const GAS u32x4*)(H + (size_t)r * D) + F.lane; GAS f32x4* op = (GAS f32x4*)(outp + (size_t)i * D);
;         u32x4 w[4]; float ss = 0.f;
; #pragma unroll
;         for (int j = 0; j < 4; ++j) { w[j] = __builtin_nontemporal_load(hp + 64 * j);
; #pragma unroll
;             for (int e = 0; e < 4; ++e) { const float x = bf_lo(w[j][e]), y = bf_hi(w[j][e]); ss += x * x + y * y; } }
;         const float rstd = 1.0f / sqrtf(wave_sum(ss) * (1.f / D) + NORM_EPS);
; #pragma unroll
;         for (int j = 0; j < 4; ++j) { const int c2 = 2 * (F.lane + 64 * j); const f32x4 g0 = *((const GAS f32x4*)g + c2), g1 = *((const GAS f32x4*)g + c2 + 1);
;             __builtin_nontemporal_store((f32x4){bf_lo(w[j].x) * rstd * g0[0], bf_hi(w[j].x) * rstd * g0[1], bf_lo(w[j].y) * rstd * g0[2], bf_hi(w[j].y) * rstd * g0[3]}, op + c2);
;             __builtin_nontemporal_store((f32x4){bf_lo(w[j].z) * rstd * g1[0], bf_hi(w[j].z) * rstd * g1[1], bf_lo(w[j].w) * rstd * g1[2], bf_hi(w[j].w) * rstd * g1[3]}, op + c2 + 1); }
.LBB0_1861:
	s_ashr_i32 s1, s0, 31
	s_lshl_b64 s[0:1], s[0:1], 12
	v_lshl_add_u64 v[26:27], v[0:1], 0, s[0:1]
	global_load_dwordx4 v[14:17], v[26:27], off nt
	global_load_dwordx4 v[18:21], v[26:27], off offset:1024 nt
	global_load_dwordx4 v[22:25], v[26:27], off offset:2048 nt
	s_nop 0
	global_load_dwordx4 v[26:29], v[26:27], off offset:3072 nt
	s_nop 0
	s_ashr_i32 s19, s18, 31
	s_lshl_b64 s[8:9], s[18:19], 13
	s_add_u32 s20, s4, s8
	s_addc_u32 s21, s5, s9
	s_add_i32 s18, s18, s14
	s_cmp_lt_i32 s18, 0x10000
	s_waitcnt vmcnt(0)
	v_lshlrev_b32_e32 v38, 16, v14
	v_and_b32_e32 v39, 0xffff0000, v14
	v_lshlrev_b32_e32 v14, 16, v15
	v_and_b32_e32 v15, 0xffff0000, v15
	v_lshlrev_b32_e32 v40, 16, v16
	v_and_b32_e32 v41, 0xffff0000, v16
	v_lshlrev_b32_e32 v42, 16, v18
	v_and_b32_e32 v43, 0xffff0000, v18
	v_lshlrev_b32_e32 v44, 16, v19
	v_and_b32_e32 v45, 0xffff0000, v19
	v_lshlrev_b32_e32 v46, 16, v20
	v_and_b32_e32 v47, 0xffff0000, v20
	v_lshlrev_b32_e32 v48, 16, v21
	v_and_b32_e32 v49, 0xffff0000, v21
	v_pk_mul_f32 v[18:19], v[38:39], v[38:39]
	v_pk_mul_f32 v[20:21], v[14:15], v[14:15]
	v_lshlrev_b32_e32 v16, 16, v17
	v_and_b32_e32 v17, 0xffff0000, v17
	v_pk_mul_f32 v[58:59], v[40:41], v[40:41]
	v_add_f32_e32 v13, v20, v21
	v_add_f32_e32 v18, v18, v19
	v_pk_mul_f32 v[60:61], v[16:17], v[16:17]
	v_add_f32_e32 v19, v58, v59
	v_add_f32_e32 v13, v18, v13
	v_pk_mul_f32 v[62:63], v[42:43], v[42:43]
	v_add_f32_e32 v20, v60, v61
	v_add_f32_e32 v13, v19, v13
	v_pk_mul_f32 v[64:65], v[44:45], v[44:45]
	v_add_f32_e32 v21, v62, v63
	v_add_f32_e32 v13, v20, v13
	v_pk_mul_f32 v[66:67], v[46:47], v[46:47]
	v_add_f32_e32 v58, v64, v65
	v_add_f32_e32 v13, v21, v13
	v_lshlrev_b32_e32 v50, 16, v22
	v_and_b32_e32 v51, 0xffff0000, v22
	v_pk_mul_f32 v[68:69], v[48:49], v[48:49]
	v_add_f32_e32 v59, v66, v67
	v_add_f32_e32 v13, v58, v13
	v_lshlrev_b32_e32 v22, 16, v23
	v_and_b32_e32 v23, 0xffff0000, v23
	v_pk_mul_f32 v[70:71], v[50:51], v[50:51]
	v_add_f32_e32 v60, v68, v69
	v_add_f32_e32 v13, v59, v13
	v_lshlrev_b32_e32 v52, 16, v24
	v_and_b32_e32 v53, 0xffff0000, v24
	v_pk_mul_f32 v[72:73], v[22:23], v[22:23]
	v_add_f32_e32 v61, v70, v71
	v_add_f32_e32 v13, v60, v13
	v_lshlrev_b32_e32 v24, 16, v25
	v_and_b32_e32 v25, 0xffff0000, v25
	v_pk_mul_f32 v[74:75], v[52:53], v[52:53]
	v_add_f32_e32 v62, v72, v73
	v_add_f32_e32 v13, v61, v13
	v_lshlrev_b32_e32 v54, 16, v26
	v_and_b32_e32 v55, 0xffff0000, v26
	v_pk_mul_f32 v[76:77], v[24:25], v[24:25]
	v_add_f32_e32 v63, v74, v75
	v_add_f32_e32 v13, v62, v13
	v_lshlrev_b32_e32 v26, 16, v27
	v_and_b32_e32 v27, 0xffff0000, v27
	v_pk_mul_f32 v[78:79], v[54:55], v[54:55]
	v_add_f32_e32 v64, v76, v77
	v_add_f32_e32 v13, v63, v13
	v_lshlrev_b32_e32 v56, 16, v28
	v_and_b32_e32 v57, 0xffff0000, v28
	v_pk_mul_f32 v[80:81], v[26:27], v[26:27]
	v_add_f32_e32 v65, v78, v79
	v_add_f32_e32 v13, v64, v13
	v_lshlrev_b32_e32 v28, 16, v29
	v_and_b32_e32 v29, 0xffff0000, v29
	v_pk_mul_f32 v[82:83], v[56:57], v[56:57]
	v_add_f32_e32 v66, v80, v81
	v_add_f32_e32 v13, v65, v13
	v_pk_mul_f32 v[84:85], v[28:29], v[28:29]
	v_add_f32_e32 v67, v82, v83
	v_add_f32_e32 v13, v66, v13
	v_add_f32_e32 v68, v84, v85
	v_add_f32_e32 v13, v67, v13
	v_add_f32_e32 v13, v68, v13
	ds_swizzle_b32 v18, v13 offset:swizzle(SWAP,1)
	s_waitcnt lgkmcnt(0)
	v_add_f32_e32 v13, v13, v18
	ds_swizzle_b32 v18, v13 offset:swizzle(SWAP,2)
	s_waitcnt lgkmcnt(0)
	v_add_f32_e32 v13, v13, v18
	ds_swizzle_b32 v18, v13 offset:swizzle(SWAP,4)
	s_waitcnt lgkmcnt(0)
	v_add_f32_e32 v13, v13, v18
	ds_swizzle_b32 v18, v13 offset:swizzle(SWAP,8)
	s_waitcnt lgkmcnt(0)
	v_add_f32_e32 v13, v13, v18
	ds_swizzle_b32 v18, v13 offset:swizzle(SWAP,16)
	s_waitcnt lgkmcnt(0)
	v_add_f32_e32 v13, v13, v18
	v_mov_b32_e32 v18, v13
	s_nop 1
	v_permlane32_swap_b32_e32 v13, v18
	v_add_f32_e32 v13, v13, v18
	v_fmamk_f32 v13, v13, 0x3a000000, v11
	v_mul_f32_e32 v18, 0x4f800000, v13
	v_cmp_gt_f32_e32 vcc, s6, v13
	s_nop 1
	v_cndmask_b32_e32 v13, v13, v18, vcc
	v_sqrt_f32_e32 v18, v13
	s_nop 0
	v_add_u32_e32 v19, -1, v18
	v_add_u32_e32 v20, 1, v18
	v_fma_f32 v21, -v19, v18, v13
	v_fma_f32 v58, -v20, v18, v13
	v_cmp_ge_f32_e64 s[0:1], 0, v21
	s_nop 1
	v_cndmask_b32_e64 v18, v18, v19, s[0:1]
	v_cmp_lt_f32_e64 s[0:1], 0, v58
	s_nop 1
	v_cndmask_b32_e64 v18, v18, v20, s[0:1]
	v_mul_f32_e32 v19, 0x37800000, v18
	v_cndmask_b32_e32 v18, v18, v19, vcc
	v_cmp_class_f32_e32 vcc, v13, v12
	s_nop 1
	v_cndmask_b32_e32 v13, v18, v13, vcc
	v_div_scale_f32 v18, s[0:1], v13, v13, 1.0
	v_rcp_f32_e32 v19, v18
	v_div_scale_f32 v20, vcc, 1.0, v13, 1.0
	v_fma_f32 v21, -v18, v19, 1.0
	v_fmac_f32_e32 v19, v21, v19
	v_mul_f32_e32 v21, v20, v19
	v_fma_f32 v58, -v18, v21, v20
	v_fmac_f32_e32 v21, v58, v19
	v_fma_f32 v18, -v18, v21, v20
	v_div_fmas_f32 v18, v18, v19, v21
	v_div_fixup_f32 v58, v18, v13, 1.0
	v_pk_mul_f32 v[18:19], v[58:59], v[38:39] op_sel_hi:[0,1]
	v_pk_mul_f32 v[14:15], v[58:59], v[14:15] op_sel_hi:[0,1]
	v_pk_mul_f32 v[38:39], v[58:59], v[40:41] op_sel_hi:[0,1]
	v_pk_mul_f32 v[20:21], v[58:59], v[16:17] op_sel_hi:[0,1]
	v_pk_mul_f32 v[16:17], v[134:135], v[14:15]
	v_pk_mul_f32 v[14:15], v[132:133], v[18:19]
	v_pk_mul_f32 v[20:21], v[130:131], v[20:21]
	v_pk_mul_f32 v[18:19], v[128:129], v[38:39]
	global_store_dwordx4 v8, v[14:17], s[20:21] nt
	global_store_dwordx4 v8, v[18:21], s[20:21] offset:16 nt
	s_nop 0
	v_pk_mul_f32 v[30:31], v[58:59], v[44:45] op_sel_hi:[0,1]
	v_pk_mul_f32 v[32:33], v[58:59], v[42:43] op_sel_hi:[0,1]
	v_pk_mul_f32 v[34:35], v[58:59], v[48:49] op_sel_hi:[0,1]
	v_pk_mul_f32 v[36:37], v[58:59], v[46:47] op_sel_hi:[0,1]
	v_pk_mul_f32 v[22:23], v[58:59], v[22:23] op_sel_hi:[0,1]
	v_pk_mul_f32 v[24:25], v[58:59], v[24:25] op_sel_hi:[0,1]
	v_pk_mul_f32 v[14:15], v[136:137], v[32:33]
	v_pk_mul_f32 v[16:17], v[138:139], v[30:31]
	v_pk_mul_f32 v[18:19], v[140:141], v[36:37]
	v_pk_mul_f32 v[20:21], v[142:143], v[34:35]
	global_store_dwordx4 v8, v[14:17], s[20:21] offset:2048 nt
	global_store_dwordx4 v8, v[18:21], s[20:21] offset:2064 nt
	s_nop 0
	v_pk_mul_f32 v[30:31], v[58:59], v[50:51] op_sel_hi:[0,1]
	v_pk_mul_f32 v[32:33], v[58:59], v[52:53] op_sel_hi:[0,1]
	v_pk_mul_f32 v[14:15], v[30:31], v[144:145]
	v_pk_mul_f32 v[16:17], v[22:23], v[146:147]
	v_pk_mul_f32 v[18:19], v[32:33], v[148:149]
	v_pk_mul_f32 v[20:21], v[24:25], v[150:151]
	global_store_dwordx4 v9, v[14:17], s[20:21] nt
	global_store_dwordx4 v9, v[18:21], s[20:21] offset:16 nt
	s_nop 0
	v_pk_mul_f32 v[22:23], v[58:59], v[26:27] op_sel_hi:[0,1]
	v_pk_mul_f32 v[24:25], v[58:59], v[54:55] op_sel_hi:[0,1]
	v_pk_mul_f32 v[26:27], v[58:59], v[28:29] op_sel_hi:[0,1]
	v_pk_mul_f32 v[28:29], v[58:59], v[56:57] op_sel_hi:[0,1]
	v_pk_mul_f32 v[14:15], v[24:25], v[152:153]
	v_pk_mul_f32 v[16:17], v[22:23], v[154:155]
	v_pk_mul_f32 v[18:19], v[28:29], v[156:157]
	v_pk_mul_f32 v[20:21], v[26:27], v[158:159]
	global_store_dwordx4 v10, v[14:17], s[20:21] nt
	global_store_dwordx4 v10, v[18:21], s[20:21] offset:16 nt
	s_cbranch_scc0 .LBB0_1866
